# K planes and hidden-activation tiles re-placed so each XCD's Q/K/V and H bytes coincide: every phase hand-off is XCD-local (no global barrier after the prologue)
# speedup vs baseline: 1.0291x; 1.0035x over previous
; __global__ void __launch_bounds__(NWAVES * 64, 2) fwd_megakernel(Args args) {
;     ...
;     const XcdBarrier bar = xcd_barrier_post((unsigned*)(args.p.ws + WS_CTL), MISC + 8);
;     {
;         const int tid = threadIdx.x, lane = tid & 63, wave = __builtin_amdgcn_readfirstlane(tid >> 6);
;         const int G = gridDim.x, bx = blockIdx.x;
;         const int vcu = (G % 8 == 0) ? (bx % 8) * (G / 8) + bx / 8 : bx;
;         prologue(args.p, lds, vcu * NWAVES + wave, G * NWAVES, wave, lane);
;     }
;     grid.sync();
;     for (int ph = 0; ph < NCHUNK * PPC; ++ph) {
;         int tid = threadIdx.x; asm volatile("" : "+v"(tid));
;         int G = gridDim.x, bx = blockIdx.x; asm volatile("" : "+s"(G), "+s"(bx));
;         const int lane = tid & 63, wave = __builtin_amdgcn_readfirstlane(tid >> 6);
;         const int vcu = (G % 8 == 0) ? (bx % 8) * (G / 8) + bx / 8 : bx;
;         const int gw = vcu * NWAVES + wave, NGW = G * NWAVES;
;         const int ck = ph / PPC, idx = ph - ck * PPC;
;         const Ph& d = args.tab[idx];
;         const int tok0 = ck * CH, grp = tok0 / GROUP_TOK, seq_len = grp ? 4096 : 2048;
;         const float* xin = args.p.x_in[grp] + (size_t)(tok0 - grp * GROUP_TOK) * D;
;         float* X = args.p.out + (size_t)tok0 * D;
.LBB0_61:
	s_or_b64 exec, exec, s[4:5]
	s_barrier
	s_load_dword s1, s[74:75], 0x668
	s_load_dwordx4 s[4:7], s[74:75], 0x60
	s_mul_i32 s2, s77, s76
	v_mbcnt_lo_u32_b32 v0, -1, 0
	v_mbcnt_hi_u32_b32 v232, -1, v0
	s_waitcnt lgkmcnt(0)
	s_mul_i32 s73, s2, s1
	s_add_u32 s54, s6, 0x6000000
	v_writelane_b32 v254, s4, 7
	s_addc_u32 s55, s7, 0
	s_add_u32 s84, s66, 0x200
	s_addc_u32 s85, s67, 0
	s_add_u32 s68, s66, 0x1000
	s_addc_u32 s69, s67, 0
	s_add_u32 s70, s66, 0x1100
	s_addc_u32 s71, s67, 0
	s_add_u32 s20, s66, 0x1200
	v_writelane_b32 v254, s5, 8
	s_addc_u32 s21, s67, 0
	v_writelane_b32 v254, s6, 9
	s_add_u32 s2, s66, 0x1300
	v_writelane_b32 v254, s7, 10
	s_addc_u32 s3, s67, 0
	v_writelane_b32 v254, s2, 11
	s_cmp_eq_u32 s0, 15
	v_and_b32_e32 v0, 64, v232
	v_writelane_b32 v254, s3, 12
	s_cselect_b64 s[2:3], -1, 0
	v_writelane_b32 v254, s2, 13
	s_cmp_eq_u32 s0, 14
	s_mov_b32 s79, 0
	v_writelane_b32 v254, s3, 14
	s_cselect_b64 s[2:3], -1, 0
	v_writelane_b32 v254, s2, 15
	s_cmp_eq_u32 s0, 13
	s_mov_b64 s[88:89], 0
	v_writelane_b32 v254, s3, 16
	s_cselect_b64 s[2:3], -1, 0
	v_writelane_b32 v254, s2, 17
	s_cmp_eq_u32 s0, 12
	s_movk_i32 s77, 0x1000
	v_writelane_b32 v254, s3, 18
	s_cselect_b64 s[2:3], -1, 0
	v_writelane_b32 v254, s2, 19
	s_cmp_eq_u32 s0, 11
	v_mov_b32_e32 v209, 0
	v_writelane_b32 v254, s3, 20
	s_cselect_b64 s[2:3], -1, 0
	v_writelane_b32 v254, s2, 21
	s_cmp_eq_u32 s0, 10
	v_mov_b32_e32 v229, 0x358637bd
	v_writelane_b32 v254, s3, 22
	s_cselect_b64 s[2:3], -1, 0
	v_writelane_b32 v254, s2, 23
	s_cmp_eq_u32 s0, 9
	s_mov_b32 s65, 0xf800000
	v_writelane_b32 v254, s3, 24
	s_cselect_b64 s[2:3], -1, 0
	v_writelane_b32 v254, s2, 25
	s_cmp_eq_u32 s0, 8
	v_mov_b32_e32 v230, 0x260
	v_writelane_b32 v254, s3, 26
	s_cselect_b64 s[2:3], -1, 0
	v_writelane_b32 v254, s2, 27
	s_cmp_eq_u32 s0, 7
	s_mov_b32 s86, 0x40000
	v_writelane_b32 v254, s3, 28
	s_cselect_b64 s[2:3], -1, 0
	v_writelane_b32 v254, s2, 29
	s_cmp_eq_u32 s0, 6
	s_mov_b32 s87, 0x41000
	v_writelane_b32 v254, s3, 30
	s_cselect_b64 s[2:3], -1, 0
	v_writelane_b32 v254, s2, 31
	s_cmp_eq_u32 s0, 5
	s_movk_i32 s91, 0x3c0
	v_writelane_b32 v254, s3, 32
	s_cselect_b64 s[2:3], -1, 0
	v_writelane_b32 v254, s2, 33
	s_cmp_eq_u32 s0, 4
	s_mov_b32 s95, 0xffffffe
	v_writelane_b32 v254, s3, 34
	s_cselect_b64 s[2:3], -1, 0
	v_writelane_b32 v254, s2, 35
	s_cmp_eq_u32 s0, 3
	s_mov_b32 s90, 0x3d800000
	v_writelane_b32 v254, s3, 36
	s_cselect_b64 s[2:3], -1, 0
	v_writelane_b32 v254, s2, 37
	s_cmp_eq_u32 s0, 2
	s_mov_b32 s92, 0x3e000000
	v_writelane_b32 v254, s3, 38
	s_cselect_b64 s[2:3], -1, 0
	v_writelane_b32 v254, s2, 39
	s_cmp_eq_u32 s0, 1
	s_mov_b32 s94, 0x3e800000
	v_writelane_b32 v254, s3, 40
	s_cselect_b64 s[2:3], -1, 0
	v_writelane_b32 v254, s2, 41
	s_cmp_eq_u32 s0, 0
	v_add_u32_e32 v233, 64, v0
	v_writelane_b32 v254, s3, 42
	s_cselect_b64 s[2:3], -1, 0
	s_lshl_b32 s0, s0, 8
	s_add_u32 s0, s66, s0
	v_writelane_b32 v254, s2, 43
	s_addc_u32 s1, s67, 0
	v_xor_b32_e32 v231, 1, v232
	v_writelane_b32 v254, s3, 44
	s_add_u32 s2, s0, 0x1400
	s_addc_u32 s3, s1, 0
	v_writelane_b32 v254, s2, 45
	s_add_u32 s0, s0, 0x2400
	s_addc_u32 s1, s1, 0
	v_writelane_b32 v254, s3, 46
	v_writelane_b32 v254, s0, 47
	v_xor_b32_e32 v253, 2, v232
	v_xor_b32_e32 v214, 4, v232
	v_writelane_b32 v254, s1, 48
	s_add_u32 s0, s66, 0x3400
	s_addc_u32 s1, s67, 0
	v_writelane_b32 v254, s0, 49
	v_xor_b32_e32 v217, 8, v232
	v_xor_b32_e32 v238, 16, v232
	v_writelane_b32 v254, s1, 50
	s_add_u32 s0, s66, 0x3500
	s_addc_u32 s1, s67, 0
	v_writelane_b32 v254, s0, 51
	v_xor_b32_e32 v239, 32, v232
	s_nop 0
	v_writelane_b32 v254, s1, 52
	s_add_i32 s0, 0, 0x21020
	v_writelane_b32 v254, s0, 53
	s_add_i32 s0, 0, 0x21024
	v_writelane_b32 v254, s0, 54
	v_writelane_b32 v254, s68, 55
	s_nop 1
	v_writelane_b32 v254, s69, 56
	v_writelane_b32 v254, s70, 57
	s_nop 1
	v_writelane_b32 v254, s71, 58
	v_writelane_b32 v254, s73, 59
	v_writelane_b32 v254, s84, 60
	s_nop 1
	v_writelane_b32 v254, s85, 61
	v_writelane_b32 v254, s20, 62
	s_nop 1
	v_writelane_b32 v254, s21, 63
	s_add_u32 s0, s66, 0x8000
	s_addc_u32 s1, s67, 0
	v_mov_b32_e32 v0, 0
	global_load_dword v1, v0, s[0:1] sc1
	global_load_dword v2, v0, s[0:1] offset:256 sc1
	global_load_dword v3, v0, s[0:1] offset:512 sc1
	global_load_dword v4, v0, s[0:1] offset:768 sc1
	global_load_dword v5, v0, s[0:1] offset:1024 sc1
	global_load_dword v6, v0, s[0:1] offset:1280 sc1
	global_load_dword v7, v0, s[0:1] offset:1536 sc1
	global_load_dword v8, v0, s[0:1] offset:1792 sc1
	s_waitcnt vmcnt(0)
	v_bcnt_u32_b32 v9, v1, 0
	v_bcnt_u32_b32 v9, v2, v9
	v_bcnt_u32_b32 v9, v3, v9
	v_bcnt_u32_b32 v9, v4, v9
	v_bcnt_u32_b32 v9, v5, v9
	v_bcnt_u32_b32 v9, v6, v9
	v_bcnt_u32_b32 v9, v7, v9
	v_bcnt_u32_b32 v9, v8, v9
	s_nop 1
	v_readfirstlane_b32 s2, v9
	s_nop 3
	s_cmp_eq_u32 s2, 8
	s_cselect_b32 s2, 7, 0
	s_cmpk_eq_i32 s76, 0x100
	s_cselect_b32 s2, s2, 0
	s_and_b32 s3, s72, s2
	v_writelane_b32 v255, s2, 20
	s_lshl_b32 s0, s3, 7
	s_add_i32 s0, s0, 0x7f
	s_cmp_lg_u32 s2, 0
	s_cselect_b32 s0, s0, 0x3ff
	v_writelane_b32 v255, s0, 21
	s_mul_i32 s0, s3, 0x60
	v_writelane_b32 v255, s0, 22
	s_cmp_lg_u32 s2, 0
	s_cselect_b32 s0, 32, s76
	v_writelane_b32 v255, s0, 23
	s_mul_i32 s0, s3, 0x300
	v_writelane_b32 v255, s0, 24
	s_and_b32 s0, s2, 3
	v_writelane_b32 v255, s0, 25
	s_branch .LBB0_65

; __device__ __forceinline__ void attn_phase(LAS unsigned char* lds, bf16* Qb, const bf16* Kb, const bf16* Vb, const float* rpb_l, int seq_len, int G, int bx, int tid, int wave, int lane) {
;     ...
;     ATT_PREFETCH();
.LBB0_89:
	s_load_dwordx2 s[8:9], s[96:97], 0x90
	s_add_i32 s7, s7, 1
	s_and_b64 s[4:5], exec, s[40:41]
	s_cselect_b32 s7, 3, s7
	s_ashr_i32 s3, s3, 8
	s_waitcnt lgkmcnt(0)
	s_add_u32 s10, s8, 0x4000000
	s_addc_u32 s11, s9, 0
	s_lshr_b32 s22, s80, 6
	s_and_b64 s[4:5], s[12:13], exec
	s_mul_i32 s17, s15, s0
	s_cselect_b32 s16, 5, 6
	s_add_i32 s4, s17, s6
	s_add_i32 s18, s22, -1
	s_ashr_i32 s5, s4, s16
	s_add_i32 s19, s16, 3
	s_and_b32 s62, s4, s18
	s_and_b32 s21, s5, 7
	s_ashr_i32 s15, s4, s19
	s_and_b64 s[4:5], s[12:13], exec
	v_sub_u32_e64 v0, s62, 4 clamp
	s_cselect_b32 s20, 11, 12
	s_add_i32 s22, s22, -8
	v_readfirstlane_b32 s4, v0
	s_min_u32 s23, s4, s22
	s_lshl_b32 s4, s21, 1
	v_lshrrev_b32_e32 v100, 4, v74
	s_add_i32 s12, s4, s3
	s_lshl_b32 s63, s15, s20
	v_lshl_or_b32 v8, s12, 3, v100
	v_lshrrev_b32_e64 v206, 12, s63
	v_lshlrev_b32_e32 v207, 7, v206
	v_sub_u32_e32 v207, v207, v206
	v_add_u32_e32 v8, v207, v8
	v_ashrrev_i32_e32 v9, 31, v8
	v_or_b32_e32 v10, s63, v98
	s_lshl_b32 s4, s62, 6
	v_lshl_add_u32 v10, s23, 6, v10
	v_lshlrev_b64 v[8:9], 16, v[8:9]
	s_add_i32 s4, s63, s4
	v_ashrrev_i32_e32 v11, 31, v10
	v_lshl_add_u64 v[8:9], s[10:11], 0, v[8:9]
	v_add_u32_e32 v0, s4, v99
	v_lshl_add_u64 v[8:9], v[10:11], 4, v[8:9]
	s_lshl_b32 s78, s14, 8
	v_ashrrev_i32_e32 v1, 31, v0
	v_lshl_add_u64 v[16:17], v[8:9], 0, s[78:79]
	s_lshl_b32 s4, s12, 6
	v_lshlrev_b64 v[0:1], 11, v[0:1]
	v_add_co_u32_e32 v24, vcc, s86, v16
	s_lshl_b32 s78, s7, 8
	s_ashr_i32 s5, s4, 31
	v_lshl_add_u64 v[0:1], s[8:9], 0, v[0:1]
	v_addc_co_u32_e32 v25, vcc, 0, v17, vcc
	v_lshl_add_u64 v[52:53], v[8:9], 0, s[78:79]
	v_lshl_add_u64 v[0:1], s[4:5], 1, v[0:1]
	v_and_b32_e32 v208, 48, v74
	v_add_co_u32_e32 v56, vcc, s86, v52
	v_lshl_add_u64 v[4:5], v[0:1], 0, v[208:209]
	s_nop 0
	v_addc_co_u32_e32 v57, vcc, 0, v53, vcc
	global_load_dwordx4 v[0:3], v[4:5], off
	s_nop 0
	global_load_dwordx4 v[4:7], v[4:5], off offset:64
	s_nop 0
	global_load_dwordx4 v[40:43], v[16:17], off
	global_load_dwordx4 v[8:11], v[16:17], off offset:1024
	global_load_dwordx4 v[44:47], v[24:25], off
	global_load_dwordx4 v[12:15], v[24:25], off offset:1024
	global_load_dwordx4 v[32:35], v[52:53], off
	global_load_dwordx4 v[20:23], v[52:53], off offset:1024
	global_load_dwordx4 v[28:31], v[56:57], off
	global_load_dwordx4 v[36:39], v[56:57], off offset:1024
	global_load_dwordx4 v[48:51], v[16:17], off offset:2048
	s_nop 0
	global_load_dwordx4 v[16:19], v[16:17], off offset:3072
	s_nop 0
	global_load_dwordx4 v[60:63], v[24:25], off offset:2048
	s_nop 0
	global_load_dwordx4 v[24:27], v[24:25], off offset:3072
	s_nop 0
	global_load_dwordx4 v[64:67], v[52:53], off offset:2048
	s_nop 0
	global_load_dwordx4 v[52:55], v[52:53], off offset:3072
	s_nop 0
	global_load_dwordx4 v[68:71], v[56:57], off offset:2048
	s_nop 0
	global_load_dwordx4 v[56:59], v[56:57], off offset:3072
	s_mul_i32 s4, s21, 0x3a2
	v_add_u32_e32 v72, s4, v188
	v_readlane_b32 s4, v255, 0
	v_ashrrev_i32_e32 v73, 31, v72
	v_readlane_b32 s5, v255, 1
	v_mov_b32_e32 v105, 0
	s_nop 0
	v_lshl_add_u64 v[72:73], v[72:73], 2, s[4:5]
	global_load_dword v75, v[72:73], off
	s_movk_i32 s4, 0x1a2
	v_cmp_gt_i32_e64 s[38:39], s4, v188
	s_and_saveexec_b64 s[12:13], s[38:39]
	s_cbranch_execz .LBB0_91
	global_load_dword v72, v[72:73], off offset:2048
	s_waitcnt vmcnt(0)
	v_mul_f32_e32 v105, 0x3fb8aa3b, v72

; #define LAS __attribute__((address_space(3)))
; __device__ __forceinline__ void attn_phase(LAS unsigned char* lds, bf16* Qb, const bf16* Kb, const bf16* Vb, const float* rpb_l, int seq_len, int G, int bx, int tid, int wave, int lane) {
;     ...
;     for (int loc = lc; loc < per; loc += nx) {
;         const int h = 2 * hp + hh;
;         const size_t qoff = (size_t)(tb + r * 64 + qc) * D + h * 64;
;         const bf16* kbase = Kb + ((size_t)(h * 8 + fq) * CH + (tb + r0 * 64 + fr)) * 8;
;         const int drb = r0 - r + 7;
;         __syncthreads();
;         {
;             const int a = wave >> 1, ub = (wave & 1) * 2;
; #pragma unroll
;             for (int i = 0; i < 16; ++i) { const int kr = 2 * (ub + (i >> 3)) + (i & 1), cb = 16 * a + 4 * ((i & 7) >> 1);
;                 const bf16* src = Vb + (size_t)(tb + (r0 + kr) * 64 + cb) * D + hp * 128 + voff[i & 3];
;                 __builtin_amdgcn_global_load_lds((const unsigned*)src, (LAS unsigned*)(lds + (wave * 16 + i) * 1024), 16, 0, 0); }
;         }
;     ...
;         for (int i = 0; i < 4; ++i) { const int kc = 16 * (sel[i] ? a0 : a1) + 4 * fq + i; bptr[i] = bias + hh * 465 + drb * 31 + min(max(kc - qc + 15, 0), 30); }
.LBB0_96:
	s_lshl_b32 s15, s23, 6
	s_lshl_b32 s64, s21, 1
	s_add_i32 s4, s15, s63
	s_add_i32 s64, s64, s3
	v_add_u32_e32 v74, s4, v98
	s_add_i32 s14, s63, s28
	s_lshl_b32 s4, s21, 8
	s_add_u32 s6, s26, s4
	s_addc_u32 s7, s27, 0
	s_add_i32 s68, s15, s30
	s_add_i32 s4, s68, s14
	s_ashr_i32 s5, s4, 31
	s_lshl_b64 s[4:5], s[4:5], 11
	s_add_u32 s12, s6, s4
	s_addc_u32 s13, s7, s5
	s_mov_b32 m0, s34
	s_waitcnt lgkmcnt(0)
	s_barrier
	global_load_lds_dwordx4 v123, s[12:13]
	s_add_i32 s12, s15, 64
	s_add_i32 s13, s12, s30
	s_add_i32 s4, s13, s14
	s_ashr_i32 s5, s4, 31
	s_lshl_b64 s[4:5], s[4:5], 11
	s_add_u32 s4, s6, s4
	s_addc_u32 s5, s7, s5
	s_mov_b32 m0, s35
	s_add_i32 s69, s14, 4
	global_load_lds_dwordx4 v124, s[4:5]
	s_add_i32 s4, s68, s69
	s_ashr_i32 s5, s4, 31
	s_lshl_b64 s[4:5], s[4:5], 11
	s_add_u32 s4, s6, s4
	s_addc_u32 s5, s7, s5
	s_add_i32 m0, s34, 0x800
	v_mfma_f32_16x16x32_bf16 v[40:43], v[40:43], v[0:3], 0
	global_load_lds_dwordx4 v125, s[4:5]
	s_add_i32 s4, s13, s69
	s_ashr_i32 s5, s4, 31
	s_lshl_b64 s[4:5], s[4:5], 11
	s_add_u32 s4, s6, s4
	s_addc_u32 s5, s7, s5
	s_mov_b32 m0, s37
	s_add_i32 s70, s14, 8
	global_load_lds_dwordx4 v126, s[4:5]
	s_add_i32 s4, s68, s70
	s_ashr_i32 s5, s4, 31
	s_lshl_b64 s[4:5], s[4:5], 11
	s_add_u32 s4, s6, s4
	s_addc_u32 s5, s7, s5
	s_add_i32 m0, s34, 0x1000
	v_mfma_f32_16x16x32_bf16 v[32:35], v[32:35], v[0:3], 0
	global_load_lds_dwordx4 v123, s[4:5]
	s_add_i32 s4, s13, s70
	s_ashr_i32 s5, s4, 31
	s_lshl_b64 s[4:5], s[4:5], 11
	s_add_u32 s4, s6, s4
	s_addc_u32 s5, s7, s5
	s_mov_b32 m0, s48
	s_add_i32 s71, s14, 12
	global_load_lds_dwordx4 v124, s[4:5]
	s_add_i32 s4, s68, s71
	s_ashr_i32 s5, s4, 31
	s_lshl_b64 s[4:5], s[4:5], 11
	s_add_u32 s4, s6, s4
	s_addc_u32 s5, s7, s5
	s_mov_b32 m0, s49
	v_mfma_f32_16x16x32_bf16 v[40:43], v[44:47], v[4:7], v[40:43]
	global_load_lds_dwordx4 v125, s[4:5]
	s_add_i32 s4, s13, s71
	s_ashr_i32 s5, s4, 31
	s_lshl_b64 s[4:5], s[4:5], 11
	s_add_u32 s4, s6, s4
	s_addc_u32 s5, s7, s5
	s_mov_b32 m0, s50
	s_add_i32 s13, s15, s31
	global_load_lds_dwordx4 v126, s[4:5]
	s_add_i32 s4, s13, s14
	s_ashr_i32 s5, s4, 31
	s_lshl_b64 s[4:5], s[4:5], 11
	s_add_u32 s4, s6, s4
	s_addc_u32 s5, s7, s5
	s_add_i32 m0, s34, 0x2000
	s_add_i32 s12, s12, s31
	global_load_lds_dwordx4 v123, s[4:5]
	s_add_i32 s4, s12, s14
	s_ashr_i32 s5, s4, 31
	s_lshl_b64 s[4:5], s[4:5], 11
	s_add_u32 s4, s6, s4
	s_addc_u32 s5, s7, s5
	s_mov_b32 m0, s51
	v_mfma_f32_16x16x32_bf16 v[28:31], v[28:31], v[4:7], v[32:35]
	global_load_lds_dwordx4 v124, s[4:5]
	s_add_i32 s4, s13, s69
	s_ashr_i32 s5, s4, 31
	s_lshl_b64 s[4:5], s[4:5], 11
	s_add_u32 s4, s6, s4
	s_addc_u32 s5, s7, s5
	s_mov_b32 m0, s52
	v_lshl_or_b32 v72, s64, 3, v100
	v_lshrrev_b32_e64 v206, 12, s63
	v_lshlrev_b32_e32 v207, 7, v206
	v_sub_u32_e32 v207, v207, v206
	v_add_u32_e32 v72, v207, v72
	global_load_lds_dwordx4 v125, s[4:5]
	s_add_i32 s4, s12, s69
	s_ashr_i32 s5, s4, 31
	s_lshl_b64 s[4:5], s[4:5], 11
	s_add_u32 s4, s6, s4
	s_addc_u32 s5, s7, s5
	s_mov_b32 m0, s56
	v_ashrrev_i32_e32 v73, 31, v72
	global_load_lds_dwordx4 v126, s[4:5]
	s_add_i32 s4, s13, s70
	s_ashr_i32 s5, s4, 31
	s_lshl_b64 s[4:5], s[4:5], 11
	s_add_u32 s4, s6, s4
	s_addc_u32 s5, s7, s5
	s_add_i32 m0, s34, 0x3000
	v_cndmask_b32_e64 v28, v28, v40, s[40:41]
	global_load_lds_dwordx4 v123, s[4:5]
	s_add_i32 s4, s12, s70
	s_ashr_i32 s5, s4, 31
	s_lshl_b64 s[4:5], s[4:5], 11
	s_add_u32 s4, s6, s4
	s_addc_u32 s5, s7, s5
	s_mov_b32 m0, s57
	v_lshlrev_b64 v[72:73], 16, v[72:73]
	global_load_lds_dwordx4 v124, s[4:5]
	s_add_i32 s4, s13, s71
	s_ashr_i32 s5, s4, 31
	s_lshl_b64 s[4:5], s[4:5], 11
	s_add_u32 s4, s6, s4
	s_addc_u32 s5, s7, s5
	s_mov_b32 m0, s58
	v_ashrrev_i32_e32 v75, 31, v74
	global_load_lds_dwordx4 v125, s[4:5]
	s_add_i32 s4, s12, s71
	s_ashr_i32 s5, s4, 31
	s_lshl_b64 s[4:5], s[4:5], 11
	s_add_u32 s4, s6, s4
	s_addc_u32 s5, s7, s5
	s_mov_b32 m0, s59
	v_lshl_add_u64 v[72:73], s[10:11], 0, v[72:73]
	global_load_lds_dwordx4 v126, s[4:5]
	s_sub_i32 s4, s23, s62
	s_mulk_i32 s4, 0x7c
	s_add_i32 s4, s29, s4
	v_lshl_add_u32 v94, v106, 2, s4
	v_lshl_add_u32 v95, v107, 2, s4
	v_lshl_add_u32 v97, v109, 2, s4
	ds_read2_b32 v[84:85], v94 offset0:217 offset1:248
	v_lshl_add_u32 v127, v110, 2, s4
	ds_read2_b32 v[88:89], v95 offset0:217 offset1:248
	ds_read2_b32 v[90:91], v97 offset0:217 offset1:248
	ds_read2_b32 v[92:93], v127 offset0:217 offset1:248
	s_waitcnt lgkmcnt(0)
; #define GAS __attribute__((address_space(1)))
; __device__ __forceinline__ void attn_phase(LAS unsigned char* lds, bf16* Qb, const bf16* Kb, const bf16* Vb, const float* rpb_l, int seq_len, int G, int bx, int tid, int wave, int lane) {
;     ...
;         for (int kr = 0; kr < 8; ++kr) {
;             f32x4 z0 = {0.f, 0.f, 0.f, 0.f}, z1 = {0.f, 0.f, 0.f, 0.f};
;             z0 = __builtin_amdgcn_mfma_f32_16x16x32_bf16(kf[kr & 3][0][0], qf0, z0, 0, 0, 0);
;             z0 = __builtin_amdgcn_mfma_f32_16x16x32_bf16(kf[kr & 3][0][1], qf1, z0, 0, 0, 0);
;             z1 = __builtin_amdgcn_mfma_f32_16x16x32_bf16(kf[kr & 3][1][0], qf0, z1, 0, 0, 0);
;             z1 = __builtin_amdgcn_mfma_f32_16x16x32_bf16(kf[kr & 3][1][1], qf1, z1, 0, 0, 0);
;             f32x4 z;
; #pragma unroll
;             for (int i = 0; i < 4; ++i) { z[i] = (sel[i] ? z0[i] : z1[i]) + bptr[i][kr * 31]; mx = fmaxf(mx, z[i]); }
;             S[kr] = z;
;             if (kr < 4) {
; #pragma unroll
;                 for (int ai = 0; ai < 2; ++ai) { const bf16* kp = kbase + ((kr + 4) * 64 + 16 * (ai ? a1 : a0)) * 8; kf[kr & 3][ai][0] = *(const GAS bf16x8*)kp; kf[kr & 3][ai][1] = *(const GAS bf16x8*)(kp + (size_t)4 * CH * 8); }
;             }
;         }
	v_add_f32_e32 v83, v84, v28
	v_cndmask_b32_e64 v28, v29, v41, s[42:43]
	v_cndmask_b32_e64 v29, v30, v42, s[44:45]
	v_add_f32_e32 v82, v28, v88
	s_mov_b32 s4, 0xff61b1e6
	v_add_f32_e32 v81, v29, v90
	v_cndmask_b32_e64 v29, v31, v43, s[46:47]
	v_lshl_add_u64 v[72:73], v[74:75], 4, v[72:73]
	v_max3_f32 v28, v83, s4, v82
	v_add_f32_e32 v80, v29, v92
	s_lshl_b32 s78, s24, 1
	v_max3_f32 v84, v28, v81, v80
	v_lshl_add_u64 v[28:29], v[72:73], 0, s[78:79]
	v_add_co_u32_e32 v78, vcc, s77, v28
	s_lshl_b32 s14, s25, 1
	s_nop 0
	v_addc_co_u32_e32 v79, vcc, 0, v29, vcc
	v_add_co_u32_e32 v76, vcc, s87, v28
	s_mov_b32 s15, s79
	s_nop 0
	v_addc_co_u32_e32 v77, vcc, 0, v29, vcc
	v_lshl_add_u64 v[28:29], v[72:73], 0, s[14:15]
	v_add_co_u32_e32 v74, vcc, s77, v28
	global_load_dwordx4 v[40:43], v[78:79], off
	global_load_dwordx4 v[44:47], v[76:77], off
	v_addc_co_u32_e32 v75, vcc, 0, v29, vcc
	global_load_dwordx4 v[32:35], v[74:75], off
	v_mfma_f32_16x16x32_bf16 v[8:11], v[8:11], v[0:3], 0
	v_add_co_u32_e32 v72, vcc, s87, v28
	v_add_u32_e32 v128, 0x400, v94
	s_nop 0
	v_addc_co_u32_e32 v73, vcc, 0, v29, vcc
	global_load_dwordx4 v[28:31], v[72:73], off
	v_mfma_f32_16x16x32_bf16 v[8:11], v[12:15], v[4:7], v[8:11]
	v_add_u32_e32 v96, 0x400, v95
	v_add_u32_e32 v97, 0x400, v97
	v_add_u32_e32 v127, 0x400, v127
	v_mfma_f32_16x16x32_bf16 v[12:15], v[20:23], v[0:3], 0
	s_cmp_lt_i32 s33, s0
	s_cselect_b64 s[12:13], -1, 0
	s_cmp_ge_i32 s33, s0
	v_mfma_f32_16x16x32_bf16 v[12:15], v[36:39], v[4:7], v[12:15]
	v_mfma_f32_16x16x32_bf16 v[48:51], v[48:51], v[0:3], 0
	v_mfma_f32_16x16x32_bf16 v[48:51], v[60:63], v[4:7], v[48:51]
	s_nop 5
	v_cndmask_b32_e64 v8, v12, v8, s[40:41]
	v_add_f32_e32 v87, v85, v8
	v_cndmask_b32_e64 v8, v13, v9, s[42:43]
	v_cndmask_b32_e64 v9, v14, v10, s[44:45]
	v_add_f32_e32 v86, v8, v89
	v_add_f32_e32 v85, v9, v91
	v_cndmask_b32_e64 v9, v15, v11, s[46:47]
	v_max3_f32 v8, v84, v87, v86
	v_add_f32_e32 v84, v9, v93
	v_max3_f32 v88, v8, v85, v84
	global_load_dwordx4 v[8:11], v[78:79], off offset:1024
	global_load_dwordx4 v[12:15], v[76:77], off offset:1024
	global_load_dwordx4 v[20:23], v[74:75], off offset:1024
	global_load_dwordx4 v[36:39], v[72:73], off offset:1024
	v_mfma_f32_16x16x32_bf16 v[60:63], v[64:67], v[0:3], 0
	ds_read2_b32 v[92:93], v128 offset0:23 offset1:54
	ds_read2_b32 v[130:131], v96 offset0:23 offset1:54
	ds_read2_b32 v[132:133], v97 offset0:23 offset1:54
	v_mfma_f32_16x16x32_bf16 v[60:63], v[68:71], v[4:7], v[60:63]
	ds_read2_b32 v[134:135], v127 offset0:23 offset1:54
	v_mfma_f32_16x16x32_bf16 v[16:19], v[16:19], v[0:3], 0
	v_mfma_f32_16x16x32_bf16 v[16:19], v[24:27], v[4:7], v[16:19]
	s_nop 4
	v_cndmask_b32_e64 v48, v60, v48, s[40:41]
	s_waitcnt lgkmcnt(0)
	v_add_f32_e32 v91, v92, v48
	v_cndmask_b32_e64 v48, v61, v49, s[42:43]
	v_cndmask_b32_e64 v49, v62, v50, s[44:45]
	v_add_f32_e32 v90, v48, v130
	v_add_f32_e32 v89, v49, v132
	v_cndmask_b32_e64 v49, v63, v51, s[46:47]
	v_max3_f32 v48, v88, v91, v90
	v_add_f32_e32 v88, v49, v134
	v_max3_f32 v92, v48, v89, v88
	global_load_dwordx4 v[48:51], v[78:79], off offset:2048
	global_load_dwordx4 v[60:63], v[76:77], off offset:2048
	global_load_dwordx4 v[64:67], v[74:75], off offset:2048
	global_load_dwordx4 v[68:71], v[72:73], off offset:2048
	v_mfma_f32_16x16x32_bf16 v[24:27], v[52:55], v[0:3], 0
	v_mfma_f32_16x16x32_bf16 v[24:27], v[56:59], v[4:7], v[24:27]
	s_nop 7
	v_cndmask_b32_e64 v16, v24, v16, s[40:41]
	v_add_f32_e32 v95, v93, v16
	v_cndmask_b32_e64 v16, v25, v17, s[42:43]
	v_cndmask_b32_e64 v17, v26, v18, s[44:45]
	v_add_f32_e32 v94, v16, v131
	v_add_f32_e32 v93, v17, v133
	v_cndmask_b32_e64 v17, v27, v19, s[46:47]
	v_max3_f32 v16, v92, v95, v94
	v_add_f32_e32 v92, v17, v135
	v_max3_f32 v129, v16, v93, v92
	global_load_dwordx4 v[16:19], v[78:79], off offset:3072
	global_load_dwordx4 v[24:27], v[76:77], off offset:3072
	global_load_dwordx4 v[52:55], v[74:75], off offset:3072
	global_load_dwordx4 v[56:59], v[72:73], off offset:3072
	s_waitcnt vmcnt(0)
	v_mfma_f32_16x16x32_bf16 v[72:75], v[40:43], v[0:3], 0
	ds_read2_b32 v[130:131], v128 offset0:85 offset1:116
	ds_read2_b32 v[132:133], v96 offset0:85 offset1:116
	ds_read2_b32 v[134:135], v97 offset0:85 offset1:116
	v_mfma_f32_16x16x32_bf16 v[76:79], v[32:35], v[0:3], 0
	ds_read2_b32 v[136:137], v127 offset0:85 offset1:116
	v_mfma_f32_16x16x32_bf16 v[72:75], v[44:47], v[4:7], v[72:75]
	v_mfma_f32_16x16x32_bf16 v[76:79], v[28:31], v[4:7], v[76:79]
	s_nop 7
	v_cndmask_b32_e64 v72, v76, v72, s[40:41]
	s_waitcnt lgkmcnt(3)
	v_add_f32_e32 v141, v130, v72
	v_cndmask_b32_e64 v72, v77, v73, s[42:43]
	s_waitcnt lgkmcnt(2)
	v_add_f32_e32 v142, v72, v132
	v_cndmask_b32_e64 v72, v78, v74, s[44:45]
	s_waitcnt lgkmcnt(1)
	v_add_f32_e32 v143, v72, v134
	v_cndmask_b32_e64 v72, v79, v75, s[46:47]
	s_waitcnt lgkmcnt(0)
	v_add_f32_e32 v136, v72, v136
	v_mfma_f32_16x16x32_bf16 v[72:75], v[8:11], v[0:3], 0
	v_mfma_f32_16x16x32_bf16 v[76:79], v[20:23], v[0:3], 0
	v_mfma_f32_16x16x32_bf16 v[72:75], v[12:15], v[4:7], v[72:75]
	v_mfma_f32_16x16x32_bf16 v[76:79], v[36:39], v[4:7], v[76:79]
	s_nop 7
	v_cndmask_b32_e64 v72, v76, v72, s[40:41]
	v_add_f32_e32 v144, v131, v72
	v_cndmask_b32_e64 v72, v77, v73, s[42:43]
	v_add_f32_e32 v145, v72, v133
	v_cndmask_b32_e64 v72, v78, v74, s[44:45]
	v_add_f32_e32 v146, v72, v135
	v_cndmask_b32_e64 v72, v79, v75, s[46:47]
	v_add_f32_e32 v137, v72, v137
	v_mfma_f32_16x16x32_bf16 v[72:75], v[48:51], v[0:3], 0
	ds_read2_b32 v[130:131], v128 offset0:147 offset1:178
	ds_read2_b32 v[132:133], v96 offset0:147 offset1:178
	ds_read2_b32 v[96:97], v97 offset0:147 offset1:178
	v_mfma_f32_16x16x32_bf16 v[76:79], v[64:67], v[0:3], 0
	ds_read2_b32 v[134:135], v127 offset0:147 offset1:178
	s_waitcnt vmcnt(0)
	s_waitcnt lgkmcnt(0)
	v_mfma_f32_16x16x32_bf16 v[72:75], v[60:63], v[4:7], v[72:75]
	s_barrier
; __device__ __forceinline__ void attn_phase(LAS unsigned char* lds, bf16* Qb, const bf16* Kb, const bf16* Vb, const float* rpb_l, int seq_len, int G, int bx, int tid, int wave, int lane) {
;     ...
;         mx = fmaxf(mx, __shfl_xor(mx, 16)); mx = fmaxf(mx, __shfl_xor(mx, 32));
;         float sum = 0.f;
; #pragma unroll
;         for (int kr = 0; kr < 8; ++kr)
; #pragma unroll
;             for (int i = 0; i < 4; ++i) { const float p = __builtin_amdgcn_exp2f(S[kr][i] - mx); S[kr][i] = p; sum += p; }
;         sum += __shfl_xor(sum, 16); sum += __shfl_xor(sum, 32);
;     ...
;         const int nloc = loc + nx; const bool has_next = nloc < per;
;         const int r_cur = r, tb_cur = tb;
;         if (has_next) { id = xc * per + nloc; r = id & (rows - 1); hp = (id >> rows_shift) & 7; tb = (id >> (rows_shift + 3)) * seq_len; r0 = min(max(r - 4, 0), rows - 8); ATT_PREFETCH(); }
	v_mfma_f32_16x16x32_bf16 v[76:79], v[68:71], v[4:7], v[76:79]
	s_nop 7
	v_cndmask_b32_e64 v72, v76, v72, s[40:41]
	v_add_f32_e32 v147, v130, v72
	v_cndmask_b32_e64 v72, v77, v73, s[42:43]
	v_add_f32_e32 v148, v72, v132
	v_cndmask_b32_e64 v72, v78, v74, s[44:45]
	v_add_f32_e32 v149, v72, v96
	v_cndmask_b32_e64 v72, v79, v75, s[46:47]
	v_add_f32_e32 v127, v72, v134
	v_mfma_f32_16x16x32_bf16 v[72:75], v[16:19], v[0:3], 0
	v_max3_f32 v96, v129, v141, v142
	v_max3_f32 v96, v96, v143, v136
	v_max3_f32 v96, v96, v144, v145
	v_mfma_f32_16x16x32_bf16 v[76:79], v[52:55], v[0:3], 0
	v_max3_f32 v96, v96, v146, v137
	v_max3_f32 v96, v96, v147, v148
	v_max3_f32 v96, v96, v149, v127
	v_mfma_f32_16x16x32_bf16 v[72:75], v[24:27], v[4:7], v[72:75]
	v_mfma_f32_16x16x32_bf16 v[76:79], v[56:59], v[4:7], v[76:79]
	s_nop 7
	v_cndmask_b32_e64 v72, v76, v72, s[40:41]
	v_cndmask_b32_e64 v73, v77, v73, s[42:43]
	v_cndmask_b32_e64 v74, v78, v74, s[44:45]
	v_add_f32_e32 v72, v131, v72
	v_add_f32_e32 v73, v73, v133
	v_add_f32_e32 v97, v74, v97
	v_cndmask_b32_e64 v74, v79, v75, s[46:47]
	v_max3_f32 v76, v96, v72, v73
	v_add_f32_e32 v150, v74, v135
	v_max3_f32 v74, v76, v97, v150
	ds_bpermute_b32 v75, v103, v74
	s_waitcnt lgkmcnt(0)
	v_max_f32_e32 v75, v75, v75
	v_max_f32_e32 v74, v74, v75
	ds_bpermute_b32 v75, v104, v74
	s_waitcnt lgkmcnt(0)
	v_max_f32_e32 v75, v75, v75
	v_max_f32_e32 v151, v74, v75
	v_sub_f32_e32 v74, v83, v151
	v_exp_f32_e32 v74, v74
	v_sub_f32_e32 v75, v82, v151
	v_exp_f32_e32 v75, v75
	v_sub_f32_e32 v77, v81, v151
	v_exp_f32_e32 v129, v77
	v_sub_f32_e32 v77, v80, v151
	v_exp_f32_e32 v130, v77
	v_sub_f32_e32 v77, v87, v151
	v_add_f32_e32 v76, 0, v74
	v_exp_f32_e32 v132, v77
	v_sub_f32_e32 v77, v86, v151
	v_add_f32_e32 v76, v75, v76
	v_exp_f32_e32 v133, v77
	v_sub_f32_e32 v77, v85, v151
	v_add_f32_e32 v76, v129, v76
	v_exp_f32_e32 v134, v77
	v_sub_f32_e32 v77, v84, v151
	v_add_f32_e32 v76, v130, v76
	v_exp_f32_e32 v135, v77
	v_sub_f32_e32 v77, v91, v151
	v_add_f32_e32 v76, v132, v76
	v_exp_f32_e32 v96, v77
	v_sub_f32_e32 v77, v90, v151
	v_add_f32_e32 v76, v133, v76
	v_exp_f32_e32 v128, v77
	v_sub_f32_e32 v77, v89, v151
	v_add_f32_e32 v76, v134, v76
	v_exp_f32_e32 v138, v77
	v_sub_f32_e32 v77, v88, v151
	v_add_f32_e32 v76, v135, v76
	v_exp_f32_e32 v139, v77
	v_sub_f32_e32 v77, v95, v151
	v_add_f32_e32 v76, v96, v76
	v_exp_f32_e32 v140, v77
	v_sub_f32_e32 v77, v94, v151
	v_add_f32_e32 v76, v128, v76
	v_exp_f32_e32 v84, v77
	v_sub_f32_e32 v77, v93, v151
	v_add_f32_e32 v76, v138, v76
	v_exp_f32_e32 v85, v77
	v_sub_f32_e32 v77, v92, v151
	v_add_f32_e32 v76, v139, v76
	v_exp_f32_e32 v131, v77
	v_sub_f32_e32 v77, v141, v151
	v_add_f32_e32 v76, v140, v76
	v_exp_f32_e32 v83, v77
	v_add_f32_e32 v76, v84, v76
	v_add_f32_e32 v76, v85, v76
	v_add_f32_e32 v76, v131, v76
	v_add_f32_e32 v77, v83, v76
	v_sub_f32_e32 v76, v142, v151
	v_exp_f32_e32 v76, v76
	v_sub_f32_e32 v87, v147, v151
	v_exp_f32_e32 v92, v87
	v_sub_f32_e32 v87, v148, v151
	v_add_f32_e32 v78, v76, v77
	v_sub_f32_e32 v77, v143, v151
	v_exp_f32_e32 v77, v77
	v_exp_f32_e32 v93, v87
	v_sub_f32_e32 v87, v149, v151
	v_exp_f32_e32 v89, v87
	v_add_f32_e32 v79, v77, v78
	v_sub_f32_e32 v78, v136, v151
	v_exp_f32_e32 v78, v78
	v_sub_f32_e32 v87, v127, v151
	v_exp_f32_e32 v90, v87
	v_sub_f32_e32 v72, v72, v151
	v_add_f32_e32 v80, v78, v79
	v_sub_f32_e32 v79, v144, v151
	v_exp_f32_e32 v79, v79
	v_exp_f32_e32 v91, v72
	v_sub_f32_e32 v73, v73, v151
	v_add_f32_e32 v81, v79, v80
	v_sub_f32_e32 v80, v145, v151
	v_exp_f32_e32 v80, v80
	s_nop 0
	v_add_f32_e32 v82, v80, v81
	v_sub_f32_e32 v81, v146, v151
	v_exp_f32_e32 v81, v81
	s_nop 0
	v_add_f32_e32 v86, v81, v82
	v_sub_f32_e32 v82, v137, v151
	v_exp_f32_e32 v82, v82
	s_nop 0
	v_add_f32_e32 v86, v82, v86
	v_add_f32_e32 v86, v92, v86
	v_add_f32_e32 v86, v93, v86
	v_add_f32_e32 v86, v89, v86
	v_add_f32_e32 v86, v90, v86
	v_add_f32_e32 v72, v91, v86
	v_exp_f32_e32 v86, v73
	v_sub_f32_e32 v73, v97, v151
	v_exp_f32_e32 v87, v73
	v_sub_f32_e32 v73, v150, v151
	v_exp_f32_e32 v88, v73
	v_add_f32_e32 v72, v86, v72
	v_add_f32_e32 v72, v87, v72
	v_add_f32_e32 v72, v88, v72
	ds_bpermute_b32 v73, v103, v72
	s_waitcnt lgkmcnt(0)
	v_add_f32_e32 v97, v72, v73
	ds_bpermute_b32 v127, v104, v97
	s_cbranch_scc1 .LBB0_100
	s_add_i32 s4, s17, s33
	s_and_b32 s60, s4, s18
	s_ashr_i32 s5, s4, s16
	s_ashr_i32 s4, s4, s19
	s_lshl_b32 s61, s4, s20
	s_max_i32 s4, s60, 4
	s_and_b32 s21, s5, 7
	s_add_i32 s4, s4, -4
	s_min_i32 s23, s4, s22
	s_lshl_b32 s4, s21, 1
	s_add_i32 s6, s4, s3
	v_lshl_or_b32 v8, s6, 3, v100
	v_lshrrev_b32_e64 v206, 12, s61
	v_lshlrev_b32_e32 v207, 7, v206
	v_sub_u32_e32 v207, v207, v206
	v_add_u32_e32 v8, v207, v8
	v_ashrrev_i32_e32 v9, 31, v8
	v_or_b32_e32 v10, s61, v98
	s_lshl_b32 s4, s60, 6
	v_lshl_add_u32 v10, s23, 6, v10
	v_lshlrev_b64 v[8:9], 16, v[8:9]
	s_add_i32 s4, s61, s4
	v_ashrrev_i32_e32 v11, 31, v10
	v_lshl_add_u64 v[8:9], s[10:11], 0, v[8:9]
	v_add_u32_e32 v0, s4, v99
	v_lshl_add_u64 v[8:9], v[10:11], 4, v[8:9]
	v_ashrrev_i32_e32 v1, 31, v0
	v_lshl_add_u64 v[16:17], v[8:9], 0, s[78:79]
	s_lshl_b32 s4, s6, 6
	v_lshlrev_b64 v[0:1], 11, v[0:1]
	v_add_co_u32_e32 v24, vcc, s86, v16
	s_ashr_i32 s5, s4, 31
	v_lshl_add_u64 v[0:1], s[8:9], 0, v[0:1]
	v_addc_co_u32_e32 v25, vcc, 0, v17, vcc
	v_lshl_add_u64 v[52:53], v[8:9], 0, s[14:15]
	v_lshl_add_u64 v[0:1], s[4:5], 1, v[0:1]
	v_lshlrev_b32_e32 v2, 1, v102
	v_mov_b32_e32 v3, v209
	v_add_co_u32_e32 v56, vcc, s86, v52
	v_lshl_add_u64 v[4:5], v[0:1], 0, v[2:3]
	s_nop 0
	v_addc_co_u32_e32 v57, vcc, 0, v53, vcc
	global_load_dwordx4 v[0:3], v[4:5], off
	s_nop 0
	global_load_dwordx4 v[4:7], v[4:5], off offset:64
	s_nop 0
	global_load_dwordx4 v[40:43], v[16:17], off
	global_load_dwordx4 v[8:11], v[16:17], off offset:1024
	global_load_dwordx4 v[44:47], v[24:25], off
	global_load_dwordx4 v[12:15], v[24:25], off offset:1024
	global_load_dwordx4 v[32:35], v[52:53], off
	global_load_dwordx4 v[20:23], v[52:53], off offset:1024
	global_load_dwordx4 v[28:31], v[56:57], off
	global_load_dwordx4 v[36:39], v[56:57], off offset:1024
	global_load_dwordx4 v[48:51], v[16:17], off offset:2048
	s_nop 0
	global_load_dwordx4 v[16:19], v[16:17], off offset:3072
	s_nop 0
	global_load_dwordx4 v[60:63], v[24:25], off offset:2048
	s_nop 0
	global_load_dwordx4 v[24:27], v[24:25], off offset:3072
	s_nop 0
	global_load_dwordx4 v[64:67], v[52:53], off offset:2048
	s_nop 0
	global_load_dwordx4 v[52:55], v[52:53], off offset:3072
	s_nop 0
	global_load_dwordx4 v[68:71], v[56:57], off offset:2048
	s_nop 0
	global_load_dwordx4 v[56:59], v[56:57], off offset:3072
	s_mul_i32 s4, s21, 0x3a2
	v_add_u32_e32 v72, s4, v188
	v_readlane_b32 s4, v255, 0
	v_ashrrev_i32_e32 v73, 31, v72
	v_readlane_b32 s5, v255, 1
	v_mov_b32_e32 v105, 0
	s_nop 0
	v_lshl_add_u64 v[72:73], v[72:73], 2, s[4:5]
	global_load_dword v175, v[72:73], off
	s_and_saveexec_b64 s[14:15], s[38:39]
	s_cbranch_execz .LBB0_99
	global_load_dword v176, v[72:73], off offset:2048

; #define LAS __attribute__((address_space(3)))
; __device__ __forceinline__ void attn_phase(LAS unsigned char* lds, bf16* Qb, const bf16* Kb, const bf16* Vb, const float* rpb_l, int seq_len, int G, int bx, int tid, int wave, int lane) {
;     ...
;         bf16x8 pf[4][2];
; #pragma unroll
;         for (int u = 0; u < 4; ++u)
; #pragma unroll
;             for (int ai = 0; ai < 2; ++ai) {
;                 float pa[2][4];
; #pragma unroll
;                 for (int t = 0; t < 2; ++t)
; #pragma unroll
;                     for (int i = 0; i < 4; ++i) pa[t][i] = (sel[i] == (ai == 0)) ? S[2 * u + t][i] : 0.f;
;                 v4u pw; pw.x = cvtpk(pa[0][0], pa[0][1]); pw.y = cvtpk(pa[0][2], pa[0][3]); pw.z = cvtpk(pa[1][0], pa[1][1]); pw.w = cvtpk(pa[1][2], pa[1][3]);
;                 pf[u][ai] = __builtin_bit_cast(bf16x8, pw); }
;         asm volatile("s_waitcnt vmcnt(0)" ::: "memory");
;         __syncthreads();
;         const int nloc = loc + nx; const bool has_next = nloc < per;
;         const int r_cur = r, tb_cur = tb;
;         if (has_next) { id = xc * per + nloc; r = id & (rows - 1); hp = (id >> rows_shift) & 7; tb = (id >> (rows_shift + 3)) * seq_len; r0 = min(max(r - 4, 0), rows - 8); ATT_PREFETCH(); }
;         (void)r_cur; (void)tb_cur;
;         f32x4 O[4];
; #pragma unroll
;         for (int c = 0; c < 4; ++c) O[c] = (f32x4){0.f, 0.f, 0.f, 0.f};
;         const LAS unsigned char* vb[2][2][4];
; #pragma unroll
;         for (int ai = 0; ai < 2; ++ai)
; #pragma unroll
;             for (int t = 0; t < 2; ++t)
; #pragma unroll
;                 for (int c = 0; c < 4; ++c) { const int rho = 8 * fq + 4 * t + q4, chn = 2 * (4 * hh + c) + (p4 >> 1);
;                     vb[ai][t][c] = lds + (ai ? a1 : a0) * 32768 + 256 * rho + 16 * (chn ^ (((rho & 3) << 2) | ((rho >> 2) & 3))) + 8 * (p4 & 1); }
; #pragma unroll
;         for (int u = 0; u < 4; ++u) {
; #pragma unroll
;             for (int ai = 0; ai < 2; ++ai) {
; #pragma unroll
;                 for (int c = 0; c < 4; ++c) {
;                     const s16x4 v0 = vtr(vb[ai][0][c] + u * 8192), v1 = vtr(vb[ai][1][c] + u * 8192);
;                     const bf16x8 vf = __builtin_shufflevector(v0, v1, 0, 1, 2, 3, 4, 5, 6, 7);
;                     O[c] = __builtin_amdgcn_mfma_f32_16x16x32_bf16(vf, pf[u][ai], O[c], 0, 0, 0);
;                 }
;             }
;         }
.LBB0_100:
	v_cndmask_b32_e64 v72, 0, v74, s[40:41]
	v_cndmask_b32_e64 v73, 0, v75, s[42:43]
	v_cndmask_b32_e64 v94, 0, v129, s[44:45]
	v_cndmask_b32_e64 v95, 0, v130, s[46:47]
	v_add_u32_e32 v144, v112, v113
	v_add_u32_e32 v143, v117, v111
	v_cndmask_b32_e64 v136, 0, v132, s[40:41]
	v_cndmask_b32_e64 v137, 0, v133, s[42:43]
	v_cndmask_b32_e64 v141, 0, v134, s[44:45]
	v_cndmask_b32_e64 v142, 0, v135, s[46:47]
	v_cvt_pk_bf16_f32 v146, v72, v73
	v_cvt_pk_bf16_f32 v147, v94, v95
	v_cndmask_b32_e64 v72, v74, 0, s[40:41]
	v_cndmask_b32_e64 v73, v75, 0, s[42:43]
	v_cndmask_b32_e64 v74, v129, 0, s[44:45]
	v_cndmask_b32_e64 v75, v130, 0, s[46:47]
	v_cndmask_b32_e64 v94, v132, 0, s[40:41]
	v_cndmask_b32_e64 v95, v133, 0, s[42:43]
	v_cndmask_b32_e64 v129, v134, 0, s[44:45]
	v_cndmask_b32_e64 v130, v135, 0, s[46:47]
	ds_read_b64_tr_b16 v[132:133], v144
	ds_read_b64_tr_b16 v[134:135], v143
	v_cvt_pk_bf16_f32 v148, v136, v137
	v_cvt_pk_bf16_f32 v149, v141, v142
	v_add_u32_e32 v142, v112, v114
	ds_read_b64_tr_b16 v[150:151], v142
	v_add_u32_e32 v141, v117, v118
	s_waitcnt lgkmcnt(1)
	v_mfma_f32_16x16x32_bf16 v[154:157], v[132:135], v[146:149], 0
	v_add_u32_e32 v137, v112, v115
	v_add_u32_e32 v136, v117, v119
	v_add_u32_e32 v135, v112, v116
	v_add_u32_e32 v134, v117, v120
	ds_read_b64_tr_b16 v[152:153], v141
	ds_read_b64_tr_b16 v[158:159], v137
	ds_read_b64_tr_b16 v[160:161], v136
	ds_read_b64_tr_b16 v[166:167], v135
	ds_read_b64_tr_b16 v[168:169], v134
	v_cvt_pk_bf16_f32 v72, v72, v73
	v_cvt_pk_bf16_f32 v73, v74, v75
	v_cvt_pk_bf16_f32 v75, v129, v130
	v_cndmask_b32_e64 v129, 0, v138, s[44:45]
	v_cndmask_b32_e64 v130, 0, v139, s[46:47]
	v_cvt_pk_bf16_f32 v163, v129, v130
	v_add_u32_e32 v133, v121, v113
	v_add_u32_e32 v132, v122, v111
	v_add_u32_e32 v130, v121, v114
	v_add_u32_e32 v129, v122, v118
	s_waitcnt lgkmcnt(4)
	v_mfma_f32_16x16x32_bf16 v[150:153], v[150:153], v[146:149], 0
	ds_read_b64_tr_b16 v[170:171], v133
	ds_read_b64_tr_b16 v[172:173], v132
	v_cvt_pk_bf16_f32 v74, v94, v95
	s_waitcnt lgkmcnt(4)
	v_mfma_f32_16x16x32_bf16 v[158:161], v[158:161], v[146:149], 0
	v_cndmask_b32_e64 v94, 0, v96, s[40:41]
	v_cndmask_b32_e64 v95, 0, v128, s[42:43]
	v_cndmask_b32_e64 v145, 0, v140, s[40:41]
	s_waitcnt lgkmcnt(2)
	v_mfma_f32_16x16x32_bf16 v[146:149], v[166:169], v[146:149], 0
	ds_read_b64_tr_b16 v[166:167], v130
	ds_read_b64_tr_b16 v[168:169], v129
	v_cndmask_b32_e64 v164, 0, v84, s[42:43]
	v_cndmask_b32_e64 v165, 0, v85, s[44:45]
	v_cndmask_b32_e64 v174, 0, v131, s[46:47]
	v_cvt_pk_bf16_f32 v162, v94, v95
	v_cvt_pk_bf16_f32 v164, v145, v164
	v_cvt_pk_bf16_f32 v165, v165, v174
	v_cndmask_b32_e64 v145, v96, 0, s[40:41]
	v_cndmask_b32_e64 v174, v128, 0, s[42:43]
	v_add_u32_e32 v128, v121, v115
	v_add_u32_e32 v96, v122, v119
	v_add_u32_e32 v95, v121, v116
	v_add_u32_e32 v94, v122, v120
	s_waitcnt lgkmcnt(2)
	v_mfma_f32_16x16x32_bf16 v[154:157], v[170:173], v[72:75], v[154:157]
	ds_read_b64_tr_b16 v[170:171], v128
	ds_read_b64_tr_b16 v[172:173], v96
	v_cndmask_b32_e64 v138, v138, 0, s[44:45]
	s_waitcnt lgkmcnt(2)
	v_mfma_f32_16x16x32_bf16 v[150:153], v[166:169], v[72:75], v[150:153]
	ds_read_b64_tr_b16 v[166:167], v95
	ds_read_b64_tr_b16 v[168:169], v94
	v_cndmask_b32_e64 v139, v139, 0, s[46:47]
	s_waitcnt lgkmcnt(2)
	v_mfma_f32_16x16x32_bf16 v[158:161], v[170:173], v[72:75], v[158:161]
	ds_read_b64_tr_b16 v[170:171], v144 offset:8192
	ds_read_b64_tr_b16 v[172:173], v143 offset:8192
	v_cndmask_b32_e64 v140, v140, 0, s[40:41]
	v_cndmask_b32_e64 v84, v84, 0, s[42:43]
	s_waitcnt lgkmcnt(2)
	v_mfma_f32_16x16x32_bf16 v[72:75], v[166:169], v[72:75], v[146:149]
	s_nop 2
	ds_read_b64_tr_b16 v[146:147], v142 offset:8192
	ds_read_b64_tr_b16 v[148:149], v141 offset:8192
	v_cndmask_b32_e64 v85, v85, 0, s[44:45]
	v_cndmask_b32_e64 v131, v131, 0, s[46:47]
	s_waitcnt lgkmcnt(2)
	v_mfma_f32_16x16x32_bf16 v[154:157], v[170:173], v[162:165], v[154:157]
	ds_read_b64_tr_b16 v[170:171], v137 offset:8192
	ds_read_b64_tr_b16 v[172:173], v136 offset:8192
	v_cvt_pk_bf16_f32 v166, v145, v174
	v_cvt_pk_bf16_f32 v167, v138, v139
	s_waitcnt lgkmcnt(2)
	v_mfma_f32_16x16x32_bf16 v[146:149], v[146:149], v[162:165], v[150:153]
	s_nop 2
	ds_read_b64_tr_b16 v[150:151], v135 offset:8192
	ds_read_b64_tr_b16 v[152:153], v134 offset:8192
	v_cvt_pk_bf16_f32 v168, v140, v84
	v_cvt_pk_bf16_f32 v169, v85, v131
	s_waitcnt lgkmcnt(2)
	v_mfma_f32_16x16x32_bf16 v[158:161], v[170:173], v[162:165], v[158:161]
	ds_read_b64_tr_b16 v[170:171], v133 offset:8192
	ds_read_b64_tr_b16 v[172:173], v132 offset:8192
	v_cndmask_b32_e64 v84, 0, v83, s[40:41]
	v_cndmask_b32_e64 v85, 0, v76, s[42:43]
	s_waitcnt lgkmcnt(2)
	v_mfma_f32_16x16x32_bf16 v[72:75], v[150:153], v[162:165], v[72:75]
	ds_read_b64_tr_b16 v[150:151], v130 offset:8192
	ds_read_b64_tr_b16 v[152:153], v129 offset:8192
	ds_read_b64_tr_b16 v[162:163], v128 offset:8192
	ds_read_b64_tr_b16 v[164:165], v96 offset:8192
	v_cndmask_b32_e64 v131, 0, v77, s[44:45]
	s_waitcnt lgkmcnt(2)
	v_mfma_f32_16x16x32_bf16 v[146:149], v[150:153], v[166:169], v[146:149]
	ds_read_b64_tr_b16 v[150:151], v95 offset:8192
	ds_read_b64_tr_b16 v[152:153], v94 offset:8192
	v_cndmask_b32_e64 v138, 0, v78, s[46:47]
	v_cndmask_b32_e64 v139, 0, v79, s[40:41]
	s_waitcnt lgkmcnt(2)
	v_mfma_f32_16x16x32_bf16 v[158:161], v[162:165], v[166:169], v[158:161]
	ds_read_b64_tr_b16 v[162:163], v144 offset:16384
	ds_read_b64_tr_b16 v[164:165], v143 offset:16384
	v_cndmask_b32_e64 v140, 0, v80, s[42:43]
	v_cndmask_b32_e64 v145, 0, v81, s[44:45]
	v_mfma_f32_16x16x32_bf16 v[154:157], v[170:173], v[166:169], v[154:157]
	v_cndmask_b32_e64 v174, 0, v82, s[46:47]
	v_cvt_pk_bf16_f32 v170, v84, v85
	v_cvt_pk_bf16_f32 v171, v131, v138
	v_cvt_pk_bf16_f32 v172, v139, v140
	v_cvt_pk_bf16_f32 v173, v145, v174
	v_cndmask_b32_e64 v84, v76, 0, s[42:43]
	v_cndmask_b32_e64 v85, v77, 0, s[44:45]
	v_cndmask_b32_e64 v131, v78, 0, s[46:47]
	s_waitcnt lgkmcnt(2)
; #define GAS __attribute__((address_space(1)))
; __device__ __forceinline__ unsigned cvtpk(float lo, float hi) { return pk2(lo, hi); }
; __device__ __forceinline__ s16x4 vtr(const LAS unsigned char* p) { return __builtin_bit_cast(s16x4, __builtin_amdgcn_ds_read_tr16_b64_v4i16((LAS s16x4*)p)); }
; #define ATT_BIAS_WRITE() do { bias[tid] = bnext[0]; if (tid + 512 < 930) bias[tid + 512] = bnext[1]; } while (0)
; __device__ __forceinline__ void attn_phase(LAS unsigned char* lds, bf16* Qb, const bf16* Kb, const bf16* Vb, const float* rpb_l, int seq_len, int G, int bx, int tid, int wave, int lane) {
;     ...
;                     const s16x4 v0 = vtr(vb[ai][0][c] + u * 8192), v1 = vtr(vb[ai][1][c] + u * 8192);
;                     const bf16x8 vf = __builtin_shufflevector(v0, v1, 0, 1, 2, 3, 4, 5, 6, 7);
;                     O[c] = __builtin_amdgcn_mfma_f32_16x16x32_bf16(vf, pf[u][ai], O[c], 0, 0, 0);
;                 }
;             }
;         }
;         const float inv = 1.0f / sum;
; #pragma unroll
;         for (int c = 0; c < 4; ++c) { v2u w; w.x = cvtpk(O[c][0] * inv, O[c][1] * inv); w.y = cvtpk(O[c][2] * inv, O[c][3] * inv);
;             *(GAS v2u*)(Qb + qoff + 16 * c + 4 * fq) = w; }
;         if (has_next) ATT_BIAS_WRITE();
	v_mfma_f32_16x16x32_bf16 v[72:75], v[150:153], v[166:169], v[72:75]
	ds_read_b64_tr_b16 v[150:151], v142 offset:16384
	ds_read_b64_tr_b16 v[152:153], v141 offset:16384
	v_cndmask_b32_e64 v138, v79, 0, s[40:41]
	v_cndmask_b32_e64 v83, v83, 0, s[40:41]
	s_waitcnt lgkmcnt(2)
	v_mfma_f32_16x16x32_bf16 v[76:79], v[162:165], v[170:173], v[154:157]
	s_nop 2
	ds_read_b64_tr_b16 v[154:155], v137 offset:16384
	ds_read_b64_tr_b16 v[156:157], v136 offset:16384
	v_cndmask_b32_e64 v139, v80, 0, s[42:43]
	v_cndmask_b32_e64 v140, v81, 0, s[44:45]
	v_cndmask_b32_e64 v145, v82, 0, s[46:47]
	v_cvt_pk_bf16_f32 v162, v83, v84
	s_waitcnt lgkmcnt(2)
	v_mfma_f32_16x16x32_bf16 v[80:83], v[150:153], v[170:173], v[146:149]
	s_nop 2
	ds_read_b64_tr_b16 v[146:147], v135 offset:16384
	ds_read_b64_tr_b16 v[148:149], v134 offset:16384
	v_cvt_pk_bf16_f32 v163, v85, v131
	v_cvt_pk_bf16_f32 v164, v138, v139
	s_waitcnt lgkmcnt(2)
	v_mfma_f32_16x16x32_bf16 v[150:153], v[154:157], v[170:173], v[158:161]
	ds_read_b64_tr_b16 v[154:155], v133 offset:16384
	ds_read_b64_tr_b16 v[156:157], v132 offset:16384
	v_cvt_pk_bf16_f32 v165, v140, v145
	v_cndmask_b32_e64 v131, 0, v92, s[40:41]
	s_waitcnt lgkmcnt(2)
	v_mfma_f32_16x16x32_bf16 v[146:149], v[146:149], v[170:173], v[72:75]
	s_nop 2
	ds_read_b64_tr_b16 v[72:73], v130 offset:16384
	ds_read_b64_tr_b16 v[74:75], v129 offset:16384
	v_cndmask_b32_e64 v138, 0, v93, s[42:43]
	v_cndmask_b32_e64 v139, 0, v89, s[44:45]
	s_waitcnt lgkmcnt(2)
	v_mfma_f32_16x16x32_bf16 v[154:157], v[154:157], v[162:165], v[76:79]
	s_nop 2
	ds_read_b64_tr_b16 v[76:77], v128 offset:16384
	ds_read_b64_tr_b16 v[78:79], v96 offset:16384
	ds_read_b64_tr_b16 v[158:159], v95 offset:16384
	ds_read_b64_tr_b16 v[160:161], v94 offset:16384
	v_cndmask_b32_e64 v140, 0, v90, s[46:47]
	s_waitcnt lgkmcnt(4)
	v_mfma_f32_16x16x32_bf16 v[82:85], v[72:75], v[162:165], v[80:83]
	v_cndmask_b32_e64 v145, 0, v91, s[40:41]
	v_cndmask_b32_e64 v166, 0, v86, s[42:43]
	v_cndmask_b32_e64 v167, 0, v87, s[44:45]
	s_waitcnt lgkmcnt(2)
	v_mfma_f32_16x16x32_bf16 v[78:81], v[76:79], v[162:165], v[150:153]
	s_nop 2
	ds_read_b64_tr_b16 v[150:151], v144 offset:24576
	ds_read_b64_tr_b16 v[152:153], v143 offset:24576
	v_cndmask_b32_e64 v72, 0, v88, s[46:47]
	v_cvt_pk_bf16_f32 v74, v131, v138
	v_cvt_pk_bf16_f32 v75, v139, v140
	v_cvt_pk_bf16_f32 v76, v145, v166
	v_cvt_pk_bf16_f32 v77, v167, v72
	ds_read_b64_tr_b16 v[138:139], v142 offset:24576
	ds_read_b64_tr_b16 v[140:141], v141 offset:24576
	s_waitcnt lgkmcnt(4)
	v_mfma_f32_16x16x32_bf16 v[144:147], v[158:161], v[162:165], v[146:149]
	v_cndmask_b32_e64 v72, v92, 0, s[40:41]
	v_cndmask_b32_e64 v73, v93, 0, s[42:43]
	v_cndmask_b32_e64 v89, v89, 0, s[44:45]
	s_waitcnt lgkmcnt(2)
	v_mfma_f32_16x16x32_bf16 v[148:151], v[150:153], v[74:77], v[154:157]
	ds_read_b64_tr_b16 v[152:153], v137 offset:24576
	s_nop 1
	ds_read_b64_tr_b16 v[154:155], v136 offset:24576
	v_cndmask_b32_e64 v131, v90, 0, s[46:47]
	v_cndmask_b32_e64 v142, v91, 0, s[40:41]
	s_waitcnt lgkmcnt(2)
	v_mfma_f32_16x16x32_bf16 v[90:93], v[138:141], v[74:77], v[82:85]
	ds_read_b64_tr_b16 v[136:137], v135 offset:24576
	ds_read_b64_tr_b16 v[138:139], v134 offset:24576
	v_cndmask_b32_e64 v134, v86, 0, s[42:43]
	v_cndmask_b32_e64 v135, v87, 0, s[44:45]
	s_waitcnt lgkmcnt(2)
	v_mfma_f32_16x16x32_bf16 v[84:87], v[152:155], v[74:77], v[78:81]
	s_nop 2
	ds_read_b64_tr_b16 v[80:81], v133 offset:24576
	ds_read_b64_tr_b16 v[82:83], v132 offset:24576
	v_cvt_pk_bf16_f32 v72, v72, v73
	v_cvt_pk_bf16_f32 v73, v89, v131
	ds_read_b64_tr_b16 v[130:131], v130 offset:24576
	ds_read_b64_tr_b16 v[132:133], v129 offset:24576
	v_cndmask_b32_e64 v88, v88, 0, s[46:47]
	s_lshl_b32 s4, s62, 6
	s_waitcnt lgkmcnt(4)
	v_mfma_f32_16x16x32_bf16 v[76:79], v[136:139], v[74:77], v[144:147]
	v_cvt_pk_bf16_f32 v74, v142, v134
	v_cvt_pk_bf16_f32 v75, v135, v88
	s_add_i32 s4, s63, s4
	v_add_f32_e32 v127, v97, v127
	ds_read_b64_tr_b16 v[134:135], v128 offset:24576
	ds_read_b64_tr_b16 v[136:137], v96 offset:24576
	v_add_u32_e32 v96, s4, v99
	s_waitcnt lgkmcnt(2)
	v_mfma_f32_16x16x32_bf16 v[88:91], v[130:133], v[72:75], v[90:93]
	s_nop 2
	ds_read_b64_tr_b16 v[92:93], v95 offset:24576
	ds_read_b64_tr_b16 v[94:95], v94 offset:24576
	v_div_scale_f32 v128, s[4:5], v127, v127, 1.0
	v_rcp_f32_e32 v129, v128
	v_mfma_f32_16x16x32_bf16 v[80:83], v[80:83], v[72:75], v[148:151]
	v_ashrrev_i32_e32 v97, 31, v96
	s_lshl_b32 s14, s64, 6
	s_ashr_i32 s15, s14, 31
	s_waitcnt lgkmcnt(2)
	v_mfma_f32_16x16x32_bf16 v[84:87], v[134:137], v[72:75], v[84:87]
	v_readlane_b32 s68, v254, 55
	v_readlane_b32 s70, v254, 57
	v_readlane_b32 s69, v254, 56
	s_waitcnt lgkmcnt(0)
	v_mfma_f32_16x16x32_bf16 v[72:75], v[92:95], v[72:75], v[76:79]
	v_readlane_b32 s71, v254, 58
	s_nop 1
	v_fma_f32 v76, -v128, v129, 1.0
	v_fmac_f32_e32 v129, v76, v129
	v_div_scale_f32 v76, vcc, 1.0, v127, 1.0
	v_mul_f32_e32 v77, v76, v129
	v_fma_f32 v78, -v128, v77, v76
	v_fmac_f32_e32 v77, v78, v129
	v_fma_f32 v76, -v128, v77, v76
	v_div_fmas_f32 v76, v76, v129, v77
	v_lshlrev_b64 v[78:79], 11, v[96:97]
	v_div_fixup_f32 v76, v76, v127, 1.0
	v_lshl_add_u64 v[78:79], s[8:9], 0, v[78:79]
	v_lshl_add_u64 v[78:79], s[14:15], 1, v[78:79]
	v_pk_mul_f32 v[80:81], v[76:77], v[80:81] op_sel_hi:[0,1]
	v_pk_mul_f32 v[82:83], v[76:77], v[82:83] op_sel_hi:[0,1]
	v_lshl_add_u64 v[78:79], v[78:79], 0, v[208:209]
	v_cvt_pk_bf16_f32 v80, v80, v81
	v_cvt_pk_bf16_f32 v81, v82, v83
	s_waitcnt vmcnt(0)
	global_store_dwordx2 v[78:79], v[80:81], off
	v_pk_mul_f32 v[80:81], v[76:77], v[88:89] op_sel_hi:[0,1]
	v_pk_mul_f32 v[82:83], v[76:77], v[90:91] op_sel_hi:[0,1]
	v_cvt_pk_bf16_f32 v80, v80, v81
	v_cvt_pk_bf16_f32 v81, v82, v83
	global_store_dwordx2 v[78:79], v[80:81], off offset:32
	v_pk_mul_f32 v[80:81], v[76:77], v[84:85] op_sel_hi:[0,1]
	v_pk_mul_f32 v[82:83], v[76:77], v[86:87] op_sel_hi:[0,1]
	v_pk_mul_f32 v[72:73], v[76:77], v[72:73] op_sel_hi:[0,1]
	v_pk_mul_f32 v[74:75], v[76:77], v[74:75] op_sel_hi:[0,1]
	v_cvt_pk_bf16_f32 v80, v80, v81
	v_cvt_pk_bf16_f32 v81, v82, v83
	v_cvt_pk_bf16_f32 v72, v72, v73
	v_cvt_pk_bf16_f32 v73, v74, v75
	s_andn2_b64 vcc, exec, s[12:13]
	s_mov_b64 s[12:13], -1
	global_store_dwordx2 v[78:79], v[80:81], off offset:64
	global_store_dwordx2 v[78:79], v[72:73], off offset:96
	s_cbranch_vccnz .LBB0_95
	v_mul_f32_e32 v108, 0x3fb8aa3b, v175
	ds_write_b32 v101, v108
	s_and_saveexec_b64 s[12:13], s[38:39]
	s_cbranch_execz .LBB0_94
	v_mul_f32_e32 v105, 0x3fb8aa3b, v176
	ds_write_b32 v101, v105 offset:2048
	s_branch .LBB0_94

; __device__ __forceinline__ unsigned cvt_pk_bf16(float lo, float hi) { unsigned r; asm volatile("v_cvt_pk_bf16_f32 %0, %1, %2" : "=v"(r) : "v"(lo), "v"(hi)); return r; }
;     __device__ __forceinline__ void operator()(const f32x4 (&acc)[2][2][4][2], const Unit& u, int wr, int wc, int fr, int fq) const {
;     ...
;         for (int ai = 0; ai < 2; ++ai)
; #pragma unroll
;             for (int m = 0; m < 4; ++m) { const int row = row0 + ai * HALF + m * 16; bf16_t* rowp = base + (size_t)row * ldc + col0;
;                 float f = sc;
;                 if (RS) { float ss = (pv[ai][m][0] + pv[ai][m][1]) + (pv[ai][m][2] + pv[ai][m][3]); ss += __shfl_xor(ss, 16); ss += __shfl_xor(ss, 32);
;                     const float r = __builtin_amdgcn_rsqf(ss * (1.0f / 1024.0f) + 1e-6f); f *= (ACT == 2) ? r * r : r; }
; #pragma unroll
;                 for (int bj = 0; bj < 2; ++bj) { f32x4 v0 = acc[ai][bj][m][0], v1 = acc[ai][bj][m][1];
;                     if (ACT == 2) {
; #pragma unroll
;                         for (int e = 0; e < 4; ++e) { const float a = fmaxf(v0[e], 0.f), b = fmaxf(v1[e], 0.f); v0[e] = a * a; v1[e] = b * b; } }
;                     v0 = v0 * f; v1 = v1 * f; u32x4 w; w.x = cvt_pk_bf16(v0[0], v0[1]); w.y = cvt_pk_bf16(v0[2], v0[3]); w.z = cvt_pk_bf16(v1[0], v1[1]); w.w = cvt_pk_bf16(v1[2], v1[3]);
;                     if (kplane) *(u32x4*)(base + ((size_t)(((colt >> 6) + 2 * bj + (wc >> 1)) * 8 + (wc & 1) * 4 + fq) * kprows + row) * 8) = w;
;                     else if (tiled) { const int r_ = row & 255, c_ = col0 + bj * HALF;
;                         *(u32x4*)((char*)base + ((size_t)(((row >> 8) * 2 + (r_ >> 7)) * (ldc >> 6) + (c_ >> 6)) << 14) + lds_byte(r_ & 127, c_ & 63)) = w; }
.LBB0_123:
	s_bfe_u32 s4, s70, 0x20002
	s_lshl_b32 s4, s4, 5
	s_lshr_b32 s5, s70, 4
	s_lshl_b32 s5, s5, 2
	s_or_b32 s4, s4, s5
	s_and_b32 s5, s70, 3
	s_or_b32 s4, s4, s5
	s_lshl_b32 s30, s4, 8
	s_add_i32 s30, s30, s51
	s_ashr_i32 s5, s30, 7
	s_lshl_b32 s4, s69, 8
	s_and_b32 s5, s5, 0x3fffffe
	v_or_b32_e32 v140, s30, v137
	s_or_b32 s4, s4, s52
	s_or_b32 s5, s5, s59
	v_lshlrev_b32_e32 v141, 6, v140
	v_lshlrev_b32_e32 v142, 2, v140
	s_lshl_b32 s28, s5, 6
	s_ashr_i32 s6, s4, 6
	v_and_or_b32 v141, v141, s91, v136
	v_and_b32_e32 v144, 32, v142
	v_max_f32_e32 v120, 0, v120
	v_max_f32_e32 v124, 0, v124
	v_max_f32_e32 v121, 0, v121
	v_max_f32_e32 v125, 0, v125
	v_max_f32_e32 v122, 0, v122
	s_add_i32 s4, s28, s6
	v_bitop3_b32 v208, v141, s62, v144 bitop3:0xde
	v_max_f32_e32 v123, 0, v123
	s_ashr_i32 s5, s4, 31
	s_or_b32 s7, s6, 2
	v_lshl_add_u64 v[142:143], s[46:47], 0, v[208:209]
	v_mul_f32_e32 v120, v120, v120
	v_mul_f32_e32 v124, v124, v124
	v_mul_f32_e32 v121, v121, v121
	v_mul_f32_e32 v125, v125, v125
	v_max_f32_e32 v126, 0, v126
	v_mul_f32_e32 v122, v122, v122
	v_max_f32_e32 v127, 0, v127
	s_lshl_b64 s[26:27], s[4:5], 14
	v_max_f32_e32 v112, 0, v112
	v_max_f32_e32 v113, 0, v113
	v_max_f32_e32 v114, 0, v114
	s_add_i32 s4, s7, s28
	v_mul_f32_e32 v123, v123, v123
	v_cvt_pk_bf16_f32 v120, v120, v121
	v_cvt_pk_bf16_f32 v121, v122, v123
	v_cvt_pk_bf16_f32 v122, v124, v125
	v_lshl_add_u64 v[124:125], v[142:143], 0, s[26:27]
	s_ashr_i32 s5, s4, 31
	v_mul_f32_e32 v126, v126, v126
	v_mul_f32_e32 v127, v127, v127
	v_cvt_pk_bf16_f32 v123, v126, v127
	global_store_dwordx4 v[124:125], v[120:123], off
	v_max_f32_e32 v116, 0, v116
	s_lshl_b64 s[28:29], s[4:5], 14
	v_mul_f32_e32 v120, v112, v112
	v_max_f32_e32 v112, 0, v117
	v_mul_f32_e32 v117, v113, v113
	v_max_f32_e32 v113, 0, v118
	v_mul_f32_e32 v118, v114, v114
	v_max_f32_e32 v114, 0, v119
	s_or_b32 s4, s30, 16
	v_max_f32_e32 v115, 0, v115
	s_lshr_b32 s4, s4, 3
	v_mul_f32_e32 v116, v116, v116
	v_mul_f32_e32 v112, v112, v112
	v_mul_f32_e32 v113, v113, v113
	v_mul_f32_e32 v114, v114, v114
	s_and_b32 s4, s4, 10
	v_max_f32_e32 v104, 0, v104
	v_max_f32_e32 v105, 0, v105
	v_max_f32_e32 v106, 0, v106
	v_mul_f32_e32 v115, v115, v115
	v_cvt_pk_bf16_f32 v112, v116, v112
	v_cvt_pk_bf16_f32 v113, v113, v114
	v_cvt_pk_bf16_f32 v114, v120, v117
	v_lshl_add_u64 v[116:117], v[142:143], 0, s[28:29]
	s_or_b32 s4, s4, s61
	v_cvt_pk_bf16_f32 v115, v118, v115
	global_store_dwordx4 v[116:117], v[112:115], off
	s_lshl_b32 s4, s4, 10
	v_max_f32_e32 v108, 0, v108
	v_mul_f32_e32 v114, v104, v104
	v_max_f32_e32 v104, 0, v109
	v_mul_f32_e32 v109, v105, v105
	v_max_f32_e32 v105, 0, v110
	v_mul_f32_e32 v110, v106, v106
	v_max_f32_e32 v106, 0, v111
	v_bitop3_b32 v208, v141, s4, v144 bitop3:0xde
	v_max_f32_e32 v107, 0, v107
	v_lshl_add_u64 v[112:113], s[46:47], 0, v[208:209]
	v_mul_f32_e32 v108, v108, v108
	v_mul_f32_e32 v104, v104, v104
	v_mul_f32_e32 v105, v105, v105
	v_mul_f32_e32 v106, v106, v106
	v_max_f32_e32 v96, 0, v96
	v_max_f32_e32 v97, 0, v97
	v_max_f32_e32 v98, 0, v98
	v_mul_f32_e32 v107, v107, v107
	v_cvt_pk_bf16_f32 v104, v108, v104
	v_cvt_pk_bf16_f32 v105, v105, v106
	v_cvt_pk_bf16_f32 v106, v114, v109
	v_lshl_add_u64 v[108:109], v[112:113], 0, s[26:27]
	v_cvt_pk_bf16_f32 v107, v110, v107
	global_store_dwordx4 v[108:109], v[104:107], off
	v_max_f32_e32 v100, 0, v100
	s_or_b32 s4, s30, 32
	v_mul_f32_e32 v104, v96, v96
	v_max_f32_e32 v96, 0, v101
	v_mul_f32_e32 v101, v97, v97
	v_max_f32_e32 v97, 0, v102
	v_mul_f32_e32 v102, v98, v98
	v_max_f32_e32 v98, 0, v103
	v_max_f32_e32 v99, 0, v99
	s_lshr_b32 s4, s4, 3
	v_mul_f32_e32 v100, v100, v100
	v_mul_f32_e32 v96, v96, v96
	v_mul_f32_e32 v97, v97, v97
	v_mul_f32_e32 v98, v98, v98
	s_and_b32 s4, s4, 12
	v_max_f32_e32 v88, 0, v88
	v_max_f32_e32 v89, 0, v89
	v_max_f32_e32 v90, 0, v90
	v_mul_f32_e32 v99, v99, v99
	v_cvt_pk_bf16_f32 v96, v100, v96
	v_cvt_pk_bf16_f32 v97, v97, v98
	v_cvt_pk_bf16_f32 v98, v104, v101
	v_lshl_add_u64 v[100:101], v[112:113], 0, s[28:29]
	s_or_b32 s4, s4, s61
	v_cvt_pk_bf16_f32 v99, v102, v99
	global_store_dwordx4 v[100:101], v[96:99], off
	s_lshl_b32 s4, s4, 10
	v_max_f32_e32 v92, 0, v92
	v_mul_f32_e32 v98, v88, v88
	v_max_f32_e32 v88, 0, v93
	v_mul_f32_e32 v93, v89, v89
	v_max_f32_e32 v89, 0, v94
	v_mul_f32_e32 v94, v90, v90
	v_max_f32_e32 v90, 0, v95
	v_bitop3_b32 v208, v141, s4, v144 bitop3:0xde
	v_max_f32_e32 v91, 0, v91
	v_lshl_add_u64 v[96:97], s[46:47], 0, v[208:209]
	v_mul_f32_e32 v92, v92, v92
	v_mul_f32_e32 v88, v88, v88
	v_mul_f32_e32 v89, v89, v89
	v_mul_f32_e32 v90, v90, v90
	v_max_f32_e32 v80, 0, v80
	v_max_f32_e32 v81, 0, v81
	v_max_f32_e32 v82, 0, v82
	v_mul_f32_e32 v91, v91, v91
	v_cvt_pk_bf16_f32 v88, v92, v88
	v_cvt_pk_bf16_f32 v89, v89, v90
	v_cvt_pk_bf16_f32 v90, v98, v93
	v_lshl_add_u64 v[92:93], v[96:97], 0, s[26:27]
	v_cvt_pk_bf16_f32 v91, v94, v91
	global_store_dwordx4 v[92:93], v[88:91], off
	v_max_f32_e32 v84, 0, v84
	s_or_b32 s4, s30, 48
	v_mul_f32_e32 v88, v80, v80
	v_max_f32_e32 v80, 0, v85
	v_mul_f32_e32 v85, v81, v81
	v_max_f32_e32 v81, 0, v86
	v_mul_f32_e32 v86, v82, v82
	v_max_f32_e32 v82, 0, v87
	v_max_f32_e32 v83, 0, v83
	s_lshr_b32 s4, s4, 3
	v_mul_f32_e32 v84, v84, v84
	v_mul_f32_e32 v80, v80, v80
	v_mul_f32_e32 v81, v81, v81
	v_mul_f32_e32 v82, v82, v82
	s_and_b32 s4, s4, 14
	v_max_f32_e32 v72, 0, v72
	v_max_f32_e32 v73, 0, v73
	v_max_f32_e32 v74, 0, v74
	v_mul_f32_e32 v83, v83, v83
	v_cvt_pk_bf16_f32 v80, v84, v80
	v_cvt_pk_bf16_f32 v81, v81, v82
	v_cvt_pk_bf16_f32 v82, v88, v85
	v_lshl_add_u64 v[84:85], v[96:97], 0, s[28:29]
	s_or_b32 s4, s4, s61
	v_cvt_pk_bf16_f32 v83, v86, v83
	global_store_dwordx4 v[84:85], v[80:83], off
; __device__ __forceinline__ unsigned cvt_pk_bf16(float lo, float hi) { unsigned r; asm volatile("v_cvt_pk_bf16_f32 %0, %1, %2" : "=v"(r) : "v"(lo), "v"(hi)); return r; }
;     __device__ __forceinline__ void operator()(const f32x4 (&acc)[2][2][4][2], const Unit& u, int wr, int wc, int fr, int fq) const {
;     ...
;                 for (int bj = 0; bj < 2; ++bj) { f32x4 v0 = acc[ai][bj][m][0], v1 = acc[ai][bj][m][1];
;                     if (ACT == 2) {
; #pragma unroll
;                         for (int e = 0; e < 4; ++e) { const float a = fmaxf(v0[e], 0.f), b = fmaxf(v1[e], 0.f); v0[e] = a * a; v1[e] = b * b; } }
;                     v0 = v0 * f; v1 = v1 * f; u32x4 w; w.x = cvt_pk_bf16(v0[0], v0[1]); w.y = cvt_pk_bf16(v0[2], v0[3]); w.z = cvt_pk_bf16(v1[0], v1[1]); w.w = cvt_pk_bf16(v1[2], v1[3]);
;                     if (kplane) *(u32x4*)(base + ((size_t)(((colt >> 6) + 2 * bj + (wc >> 1)) * 8 + (wc & 1) * 4 + fq) * kprows + row) * 8) = w;
;                     else if (tiled) { const int r_ = row & 255, c_ = col0 + bj * HALF;
;                         *(u32x4*)((char*)base + ((size_t)(((row >> 8) * 2 + (r_ >> 7)) * (ldc >> 6) + (c_ >> 6)) << 14) + lds_byte(r_ & 127, c_ & 63)) = w; }
	s_lshl_b32 s4, s4, 10
	v_max_f32_e32 v76, 0, v76
	v_mul_f32_e32 v82, v72, v72
	v_max_f32_e32 v72, 0, v77
	v_mul_f32_e32 v77, v73, v73
	v_max_f32_e32 v73, 0, v78
	v_mul_f32_e32 v78, v74, v74
	v_max_f32_e32 v74, 0, v79
	v_bitop3_b32 v208, v141, s4, v144 bitop3:0xde
	v_max_f32_e32 v75, 0, v75
	v_lshl_add_u64 v[80:81], s[46:47], 0, v[208:209]
	v_mul_f32_e32 v76, v76, v76
	v_mul_f32_e32 v72, v72, v72
	v_mul_f32_e32 v73, v73, v73
	v_mul_f32_e32 v74, v74, v74
	v_max_f32_e32 v64, 0, v64
	v_max_f32_e32 v65, 0, v65
	v_max_f32_e32 v66, 0, v66
	v_mul_f32_e32 v75, v75, v75
	v_cvt_pk_bf16_f32 v72, v76, v72
	v_cvt_pk_bf16_f32 v73, v73, v74
	v_cvt_pk_bf16_f32 v74, v82, v77
	v_lshl_add_u64 v[76:77], v[80:81], 0, s[26:27]
	v_cvt_pk_bf16_f32 v75, v78, v75
	global_store_dwordx4 v[76:77], v[72:75], off
	v_max_f32_e32 v68, 0, v68
	s_nop 0
	v_mul_f32_e32 v72, v64, v64
	v_max_f32_e32 v64, 0, v69
	v_mul_f32_e32 v69, v65, v65
	v_max_f32_e32 v65, 0, v70
	v_mul_f32_e32 v70, v66, v66
	v_max_f32_e32 v66, 0, v71
	v_max_f32_e32 v67, 0, v67
	v_mul_f32_e32 v68, v68, v68
	v_mul_f32_e32 v64, v64, v64
	v_mul_f32_e32 v65, v65, v65
	v_mul_f32_e32 v66, v66, v66
	v_mul_f32_e32 v67, v67, v67
	v_cvt_pk_bf16_f32 v64, v68, v64
	v_cvt_pk_bf16_f32 v65, v65, v66
	v_cvt_pk_bf16_f32 v66, v72, v69
	v_lshl_add_u64 v[68:69], v[80:81], 0, s[28:29]
	v_max_f32_e32 v56, 0, v56
	v_cvt_pk_bf16_f32 v67, v70, v67
	global_store_dwordx4 v[68:69], v[64:67], off
	v_max_f32_e32 v57, 0, v57
	s_nop 0
	v_add_u32_e32 v64, 0x80, v140
	v_max_f32_e32 v58, 0, v58
	v_ashrrev_i32_e32 v65, 7, v64
	v_bfe_u32 v66, v64, 7, 1
	s_mov_b32 s4, 0x3fffffe
	v_max_f32_e32 v60, 0, v60
	v_mul_f32_e32 v67, v56, v56
	v_max_f32_e32 v56, 0, v61
	v_and_or_b32 v66, v65, s4, v66
	v_mul_f32_e32 v61, v57, v57
	v_max_f32_e32 v57, 0, v62
	v_mul_f32_e32 v62, v58, v58
	v_max_f32_e32 v58, 0, v63
	v_lshlrev_b32_e32 v65, 6, v64
	v_lshlrev_b32_e32 v64, 2, v64
	v_mul_f32_e32 v60, v60, v60
	v_mul_f32_e32 v56, v56, v56
	v_lshlrev_b32_e32 v66, 6, v66
	v_and_or_b32 v65, v65, s91, v136
	v_and_b32_e32 v64, 32, v64
	v_mul_f32_e32 v57, v57, v57
	v_max_f32_e32 v59, 0, v59
	v_mul_f32_e32 v58, v58, v58
	v_cvt_pk_bf16_f32 v56, v60, v56
	v_add_u32_e32 v60, s6, v66
	v_bitop3_b32 v208, v65, s62, v64 bitop3:0xde
	v_cvt_pk_bf16_f32 v57, v57, v58
	v_cvt_pk_bf16_f32 v58, v67, v61
	v_ashrrev_i32_e32 v61, 31, v60
	v_lshl_add_u64 v[64:65], s[46:47], 0, v[208:209]
	v_mul_f32_e32 v59, v59, v59
	v_lshlrev_b64 v[60:61], 14, v[60:61]
	v_max_f32_e32 v48, 0, v48
	v_cvt_pk_bf16_f32 v59, v62, v59
	v_lshl_add_u64 v[62:63], v[64:65], 0, v[60:61]
	v_max_f32_e32 v49, 0, v49
	v_max_f32_e32 v50, 0, v50
	global_store_dwordx4 v[62:63], v[56:59], off
	v_max_f32_e32 v52, 0, v52
	s_nop 0
	v_mul_f32_e32 v56, v48, v48
	v_max_f32_e32 v48, 0, v53
	v_mul_f32_e32 v53, v49, v49
	v_max_f32_e32 v49, 0, v54
	v_mul_f32_e32 v54, v50, v50
	v_max_f32_e32 v50, 0, v55
	v_mul_f32_e32 v52, v52, v52
	v_mul_f32_e32 v48, v48, v48
	v_mul_f32_e32 v49, v49, v49
	v_max_f32_e32 v51, 0, v51
	v_mul_f32_e32 v50, v50, v50
	v_cvt_pk_bf16_f32 v48, v52, v48
	v_add_u32_e32 v52, s7, v66
	v_cvt_pk_bf16_f32 v49, v49, v50
	v_cvt_pk_bf16_f32 v50, v56, v53
	v_ashrrev_i32_e32 v53, 31, v52
	v_mul_f32_e32 v51, v51, v51
	v_lshlrev_b64 v[52:53], 14, v[52:53]
	v_cvt_pk_bf16_f32 v51, v54, v51
	v_lshl_add_u64 v[54:55], v[64:65], 0, v[52:53]
	global_store_dwordx4 v[54:55], v[48:51], off
	v_max_f32_e32 v40, 0, v40
	v_max_f32_e32 v41, 0, v41
	v_add_u32_e32 v48, 0x90, v140
	v_lshrrev_b32_e32 v49, 3, v48
	v_and_or_b32 v49, v49, 10, s61
	v_lshlrev_b32_e32 v50, 6, v48
	v_lshlrev_b32_e32 v48, 2, v48
	v_max_f32_e32 v42, 0, v42
	v_and_or_b32 v50, v50, s91, v136
	v_lshlrev_b32_e32 v49, 10, v49
	v_and_b32_e32 v48, 32, v48
	v_bitop3_b32 v208, v50, v49, v48 bitop3:0xde
	v_max_f32_e32 v44, 0, v44
	v_mul_f32_e32 v50, v40, v40
	v_max_f32_e32 v40, 0, v45
	v_mul_f32_e32 v45, v41, v41
	v_max_f32_e32 v41, 0, v46
	v_mul_f32_e32 v46, v42, v42
	v_max_f32_e32 v42, 0, v47
	v_max_f32_e32 v43, 0, v43
	v_lshl_add_u64 v[48:49], s[46:47], 0, v[208:209]
	v_mul_f32_e32 v44, v44, v44
	v_mul_f32_e32 v40, v40, v40
	v_mul_f32_e32 v41, v41, v41
	v_mul_f32_e32 v42, v42, v42
	v_max_f32_e32 v32, 0, v32
	v_max_f32_e32 v33, 0, v33
	v_max_f32_e32 v34, 0, v34
	v_mul_f32_e32 v43, v43, v43
	v_cvt_pk_bf16_f32 v40, v44, v40
; __device__ __forceinline__ unsigned cvt_pk_bf16(float lo, float hi) { unsigned r; asm volatile("v_cvt_pk_bf16_f32 %0, %1, %2" : "=v"(r) : "v"(lo), "v"(hi)); return r; }
; #define PG8_BAR __builtin_amdgcn_s_barrier()
;     __device__ __forceinline__ void operator()(const f32x4 (&acc)[2][2][4][2], const Unit& u, int wr, int wc, int fr, int fq) const {
;     ...
;                 for (int bj = 0; bj < 2; ++bj) { f32x4 v0 = acc[ai][bj][m][0], v1 = acc[ai][bj][m][1];
;                     if (ACT == 2) {
; #pragma unroll
;                         for (int e = 0; e < 4; ++e) { const float a = fmaxf(v0[e], 0.f), b = fmaxf(v1[e], 0.f); v0[e] = a * a; v1[e] = b * b; } }
;                     v0 = v0 * f; v1 = v1 * f; u32x4 w; w.x = cvt_pk_bf16(v0[0], v0[1]); w.y = cvt_pk_bf16(v0[2], v0[3]); w.z = cvt_pk_bf16(v1[0], v1[1]); w.w = cvt_pk_bf16(v1[2], v1[3]);
;                     if (kplane) *(u32x4*)(base + ((size_t)(((colt >> 6) + 2 * bj + (wc >> 1)) * 8 + (wc & 1) * 4 + fq) * kprows + row) * 8) = w;
;                     else if (tiled) { const int r_ = row & 255, c_ = col0 + bj * HALF;
;                         *(u32x4*)((char*)base + ((size_t)(((row >> 8) * 2 + (r_ >> 7)) * (ldc >> 6) + (c_ >> 6)) << 14) + lds_byte(r_ & 127, c_ & 63)) = w; }
;                     else *(u32x4*)(rowp + bj * HALF) = w; } }
; template <class Epi, class Sched, bool ALIGN_EPI = false, bool SP2 = false>
; __device__ __forceinline__ void gemm_phase(PG8_LAS unsigned char* lds, const Gemm g, const Sched& S, const Epi& E, const int tid_in) {
;     ...
;         if constexpr (ALIGN_EPI) { if (wr == 0) PG8_BAR; }
;         if constexpr (!Epi::AFTER_DRAIN) { E(acc, cur, wr, wc, fr, fq); S.done(cur); }
;         if (!has_next) break;
; #pragma unroll
;         for (int a = 0; a < 2; ++a)
; #pragma unroll
;             for (int b = 0; b < 2; ++b)
; #pragma unroll
;                 for (int m = 0; m < 4; ++m)
; #pragma unroll
;                     for (int n = 0; n < 2; ++n) acc[a][b][m][n] = (f32x4){0.f, 0.f, 0.f, 0.f};
;         cur = nxt; cA = nA; cB = nB; ++ui;
;         if constexpr (ALIGN_EPI) { if (wr == 1) PG8_BAR; }
	v_cvt_pk_bf16_f32 v41, v41, v42
	v_cvt_pk_bf16_f32 v42, v50, v45
	v_lshl_add_u64 v[44:45], v[48:49], 0, v[60:61]
	v_cvt_pk_bf16_f32 v43, v46, v43
	global_store_dwordx4 v[44:45], v[40:43], off
	v_max_f32_e32 v36, 0, v36
	s_nop 0
	v_mul_f32_e32 v40, v32, v32
	v_max_f32_e32 v32, 0, v37
	v_mul_f32_e32 v37, v33, v33
	v_max_f32_e32 v33, 0, v38
	v_mul_f32_e32 v38, v34, v34
	v_max_f32_e32 v34, 0, v39
	v_max_f32_e32 v35, 0, v35
	v_mul_f32_e32 v36, v36, v36
	v_mul_f32_e32 v32, v32, v32
	v_mul_f32_e32 v33, v33, v33
	v_mul_f32_e32 v34, v34, v34
	v_mul_f32_e32 v35, v35, v35
	v_cvt_pk_bf16_f32 v32, v36, v32
	v_cvt_pk_bf16_f32 v33, v33, v34
	v_cvt_pk_bf16_f32 v34, v40, v37
	v_lshl_add_u64 v[36:37], v[48:49], 0, v[52:53]
	v_cvt_pk_bf16_f32 v35, v38, v35
	global_store_dwordx4 v[36:37], v[32:35], off
	v_max_f32_e32 v24, 0, v24
	v_max_f32_e32 v25, 0, v25
	v_add_u32_e32 v32, 0xa0, v140
	v_lshrrev_b32_e32 v33, 3, v32
	v_and_or_b32 v33, v33, 12, s61
	v_lshlrev_b32_e32 v34, 6, v32
	v_lshlrev_b32_e32 v32, 2, v32
	v_max_f32_e32 v26, 0, v26
	v_and_or_b32 v34, v34, s91, v136
	v_lshlrev_b32_e32 v33, 10, v33
	v_and_b32_e32 v32, 32, v32
	v_bitop3_b32 v208, v34, v33, v32 bitop3:0xde
	v_max_f32_e32 v28, 0, v28
	v_mul_f32_e32 v34, v24, v24
	v_max_f32_e32 v24, 0, v29
	v_mul_f32_e32 v29, v25, v25
	v_max_f32_e32 v25, 0, v30
	v_mul_f32_e32 v30, v26, v26
	v_max_f32_e32 v26, 0, v31
	v_max_f32_e32 v27, 0, v27
	v_lshl_add_u64 v[32:33], s[46:47], 0, v[208:209]
	v_mul_f32_e32 v28, v28, v28
	v_mul_f32_e32 v24, v24, v24
	v_mul_f32_e32 v25, v25, v25
	v_mul_f32_e32 v26, v26, v26
	v_max_f32_e32 v16, 0, v16
	v_max_f32_e32 v17, 0, v17
	v_max_f32_e32 v18, 0, v18
	v_mul_f32_e32 v27, v27, v27
	v_cvt_pk_bf16_f32 v24, v28, v24
	v_cvt_pk_bf16_f32 v25, v25, v26
	v_cvt_pk_bf16_f32 v26, v34, v29
	v_lshl_add_u64 v[28:29], v[32:33], 0, v[60:61]
	v_cvt_pk_bf16_f32 v27, v30, v27
	global_store_dwordx4 v[28:29], v[24:27], off
	v_max_f32_e32 v20, 0, v20
	s_nop 0
	v_mul_f32_e32 v24, v16, v16
	v_max_f32_e32 v16, 0, v21
	v_mul_f32_e32 v21, v17, v17
	v_max_f32_e32 v17, 0, v22
	v_mul_f32_e32 v22, v18, v18
	v_max_f32_e32 v18, 0, v23
	v_max_f32_e32 v19, 0, v19
	v_mul_f32_e32 v20, v20, v20
	v_mul_f32_e32 v16, v16, v16
	v_mul_f32_e32 v17, v17, v17
	v_mul_f32_e32 v18, v18, v18
	v_mul_f32_e32 v19, v19, v19
	v_cvt_pk_bf16_f32 v16, v20, v16
	v_cvt_pk_bf16_f32 v17, v17, v18
	v_cvt_pk_bf16_f32 v18, v24, v21
	v_lshl_add_u64 v[20:21], v[32:33], 0, v[52:53]
	v_cvt_pk_bf16_f32 v19, v22, v19
	global_store_dwordx4 v[20:21], v[16:19], off
	v_max_f32_e32 v8, 0, v8
	v_max_f32_e32 v9, 0, v9
	v_add_u32_e32 v16, 0xb0, v140
	v_lshrrev_b32_e32 v17, 3, v16
	v_and_or_b32 v17, v17, 14, s61
	v_lshlrev_b32_e32 v18, 6, v16
	v_lshlrev_b32_e32 v16, 2, v16
	v_max_f32_e32 v10, 0, v10
	v_and_or_b32 v18, v18, s91, v136
	v_lshlrev_b32_e32 v17, 10, v17
	v_and_b32_e32 v16, 32, v16
	v_bitop3_b32 v208, v18, v17, v16 bitop3:0xde
	v_max_f32_e32 v12, 0, v12
	v_mul_f32_e32 v18, v8, v8
	v_max_f32_e32 v8, 0, v13
	v_mul_f32_e32 v13, v9, v9
	v_max_f32_e32 v9, 0, v14
	v_mul_f32_e32 v14, v10, v10
	v_max_f32_e32 v10, 0, v15
	v_max_f32_e32 v11, 0, v11
	v_lshl_add_u64 v[16:17], s[46:47], 0, v[208:209]
	v_mul_f32_e32 v12, v12, v12
	v_mul_f32_e32 v8, v8, v8
	v_mul_f32_e32 v9, v9, v9
	v_mul_f32_e32 v10, v10, v10
	v_max_f32_e32 v0, 0, v0
	v_max_f32_e32 v1, 0, v1
	v_max_f32_e32 v2, 0, v2
	v_mul_f32_e32 v11, v11, v11
	v_cvt_pk_bf16_f32 v8, v12, v8
	v_cvt_pk_bf16_f32 v9, v9, v10
	v_cvt_pk_bf16_f32 v10, v18, v13
	v_lshl_add_u64 v[12:13], v[16:17], 0, v[60:61]
	v_cvt_pk_bf16_f32 v11, v14, v11
	global_store_dwordx4 v[12:13], v[8:11], off
	v_max_f32_e32 v4, 0, v4
	s_nop 0
	v_mul_f32_e32 v8, v0, v0
	v_max_f32_e32 v0, 0, v5
	v_mul_f32_e32 v5, v1, v1
	v_max_f32_e32 v1, 0, v6
	v_mul_f32_e32 v6, v2, v2
	v_max_f32_e32 v2, 0, v7
	v_max_f32_e32 v3, 0, v3
	v_mul_f32_e32 v4, v4, v4
	v_mul_f32_e32 v0, v0, v0
	v_mul_f32_e32 v1, v1, v1
	v_mul_f32_e32 v2, v2, v2
	v_mul_f32_e32 v3, v3, v3
	v_cvt_pk_bf16_f32 v0, v4, v0
	v_cvt_pk_bf16_f32 v1, v1, v2
	v_cvt_pk_bf16_f32 v2, v8, v5
	v_lshl_add_u64 v[4:5], v[16:17], 0, v[52:53]
	s_and_b64 vcc, exec, s[38:39]
	s_mov_b64 s[26:27], -1
	v_cvt_pk_bf16_f32 v3, v6, v3
	global_store_dwordx4 v[4:5], v[0:3], off
	s_cbranch_vccnz .LBB0_111
	s_andn2_b64 vcc, exec, s[16:17]
	s_cbranch_vccnz .LBB0_110
	s_barrier
	s_branch .LBB0_110

;     __device__ __forceinline__ void operator()(const f32x4 (&acc)[2][2][4][2], const Unit& u, int wr, int wc, int fr, int fq) const {
;         const int row0 = u.pm * BM + wr * 64 + fr; int colt = u.pn * BM; bf16_t* base = O;
;         float sc = 1.f; bool kplane = false;
;         if (split_cols) { const int t = colt / split_cols; base += (size_t)t * split_stride; colt -= t * split_cols; if (t == 0) sc = scale0; kplane = (t == 1); }
;         const size_t kprows = split_stride / 1024;
;         const int col0 = colt + wc * 32 + 8 * fq;
;         f32x4 pv[2][4];
;         if (RS) {
; #pragma unroll
;             for (int ai = 0; ai < 2; ++ai)
; #pragma unroll
;                 for (int m = 0; m < 4; ++m) pv[ai][m] = *(const f32x4*)(st + (size_t)(row0 + ai * HALF + m * 16) * 16 + 4 * fq);
;             __builtin_amdgcn_sched_barrier(0);
;         }
; #pragma unroll
;         for (int ai = 0; ai < 2; ++ai)
; #pragma unroll
;             for (int m = 0; m < 4; ++m) { const int row = row0 + ai * HALF + m * 16; bf16_t* rowp = base + (size_t)row * ldc + col0;
;                 float f = sc;
;                 if (RS) { float ss = (pv[ai][m][0] + pv[ai][m][1]) + (pv[ai][m][2] + pv[ai][m][3]); ss += __shfl_xor(ss, 16); ss += __shfl_xor(ss, 32);
;                     const float r = __builtin_amdgcn_rsqf(ss * (1.0f / 1024.0f) + 1e-6f); f *= (ACT == 2) ? r * r : r; }
;     ...
;                     if (kplane) *(u32x4*)(base + ((size_t)(((colt >> 6) + 2 * bj + (wc >> 1)) * 8 + (wc & 1) * 4 + fq) * kprows + row) * 8) = w;
.LBB0_148:
	v_lshrrev_b32_e64 v218, 4, s63
	v_lshlrev_b32_e32 v219, 7, v218
	v_sub_u32_e32 v219, v219, v218
	v_lshl_add_u32 v182, s63, 8, v189
	v_or_b32_e32 v180, 16, v182
	v_ashrrev_i32_e32 v183, 31, v182
	v_ashrrev_i32_e32 v181, 31, v180
	v_lshlrev_b64 v[128:129], 6, v[182:183]
	v_lshlrev_b64 v[130:131], 6, v[180:181]
	v_or_b32_e32 v178, 32, v182
	v_or_b32_e32 v176, 48, v182
	v_lshl_add_u64 v[128:129], v[160:161], 0, v[128:129]
	v_lshl_add_u64 v[130:131], v[160:161], 0, v[130:131]
	v_ashrrev_i32_e32 v179, 31, v178
	v_ashrrev_i32_e32 v177, 31, v176
	global_load_dwordx4 v[184:187], v[128:129], off
	global_load_dwordx4 v[152:155], v[130:131], off
	v_lshlrev_b64 v[128:129], 6, v[178:179]
	v_lshlrev_b64 v[130:131], 6, v[176:177]
	v_add_u32_e32 v174, 0x80, v182
	v_add_u32_e32 v172, 0x90, v182
	v_lshl_add_u64 v[128:129], v[160:161], 0, v[128:129]
	v_lshl_add_u64 v[130:131], v[160:161], 0, v[130:131]
	v_ashrrev_i32_e32 v175, 31, v174
	v_ashrrev_i32_e32 v173, 31, v172
	global_load_dwordx4 v[148:151], v[128:129], off
	global_load_dwordx4 v[144:147], v[130:131], off
	v_lshlrev_b64 v[128:129], 6, v[174:175]
	v_lshlrev_b64 v[130:131], 6, v[172:173]
	v_add_u32_e32 v168, 0xa0, v182
	v_add_u32_e32 v166, 0xb0, v182
	v_lshl_add_u64 v[128:129], v[160:161], 0, v[128:129]
	v_lshl_add_u64 v[130:131], v[160:161], 0, v[130:131]
	v_ashrrev_i32_e32 v169, 31, v168
	v_ashrrev_i32_e32 v167, 31, v166
	global_load_dwordx4 v[140:143], v[128:129], off
	global_load_dwordx4 v[136:139], v[130:131], off
	v_lshlrev_b64 v[128:129], 6, v[168:169]
	v_lshlrev_b64 v[130:131], 6, v[166:167]
	v_lshl_add_u64 v[128:129], v[160:161], 0, v[128:129]
	v_lshl_add_u64 v[130:131], v[160:161], 0, v[130:131]
	global_load_dwordx4 v[132:135], v[128:129], off
	s_nop 0
	global_load_dwordx4 v[128:131], v[130:131], off
	s_ashr_i32 s4, s62, 31
	s_lshr_b32 s4, s4, 30
	s_add_i32 s4, s62, s4
	s_ashr_i32 s4, s4, 2
	s_ashr_i32 s5, s4, 31
	s_lshl_b32 s28, s62, 8
	s_lshl_b64 s[6:7], s[4:5], 26
	s_add_u32 s26, s46, s6
	s_addc_u32 s27, s47, s7
	s_lshl_b32 s4, s4, 10
	s_sub_i32 s6, s28, s4
	s_add_i32 s4, s62, 3
	s_cmp_lt_u32 s4, 7
	s_cselect_b64 vcc, -1, 0
	s_and_b32 s4, s62, -4
	v_mov_b32_e32 v170, 0x3e38aa3b
	s_cmp_lg_u32 s4, 4
	v_cndmask_b32_e32 v195, 1.0, v170, vcc
	s_cselect_b64 s[28:29], -1, 0
	v_or_b32_e32 v170, s6, v191
	v_cmp_lt_i32_e32 vcc, v238, v233
	s_waitcnt vmcnt(0)
	v_mov_b32_e32 v198, v185
	v_mov_b32_e32 v199, v186
	v_mov_b32_e32 v185, v187
	v_cndmask_b32_e32 v171, v232, v238, vcc
	v_pk_add_f32 v[184:185], v[198:199], v[184:185]
	v_lshlrev_b32_e32 v196, 2, v171
	v_add_f32_e32 v171, v184, v185
	ds_bpermute_b32 v184, v196, v171
	v_cmp_lt_i32_e32 vcc, v239, v233
	s_mov_b64 s[30:31], -1
	s_waitcnt lgkmcnt(0)
	v_add_f32_e32 v184, v171, v184
	v_cndmask_b32_e32 v185, v232, v239, vcc
	v_lshlrev_b32_e32 v197, 2, v185
	ds_bpermute_b32 v185, v197, v184
	v_ashrrev_i32_e32 v171, 31, v170
	v_lshl_add_u64 v[170:171], v[170:171], 1, s[26:27]
	s_and_b64 vcc, exec, s[28:29]
	s_waitcnt lgkmcnt(0)
	v_add_f32_e32 v184, v184, v185
	v_fmamk_f32 v184, v184, 0x3a800000, v229
	v_rsq_f32_e32 v186, v184
	v_lshlrev_b64 v[184:185], 11, v[182:183]
	v_lshl_add_u64 v[184:185], v[170:171], 0, v[184:185]
	v_mul_f32_e32 v186, v195, v186
	v_pk_mul_f32 v[198:199], v[122:123], v[186:187] op_sel_hi:[1,0]
	v_pk_mul_f32 v[122:123], v[120:121], v[186:187] op_sel_hi:[1,0]
	v_pk_mul_f32 v[126:127], v[126:127], v[186:187] op_sel_hi:[1,0]
	v_pk_mul_f32 v[124:125], v[124:125], v[186:187] op_sel_hi:[1,0]
	s_nop 0
	v_cvt_pk_bf16_f32 v120, v124, v125
	v_cvt_pk_bf16_f32 v121, v126, v127
	v_cvt_pk_bf16_f32 v122, v122, v123
	v_cvt_pk_bf16_f32 v123, v198, v199
	s_cbranch_vccz .LBB0_150
	global_store_dwordx4 v[184:185], v[120:123], off
	s_mov_b64 s[30:31], 0
.LBB0_150:
	s_ashr_i32 s4, s6, 6
	s_or_b32 s6, s4, s48
	s_andn2_b64 vcc, exec, s[30:31]
	v_lshl_or_b32 v208, s6, 3, v192
	v_add_u32_e32 v208, v219, v208
	s_cbranch_vccnz .LBB0_152
	v_lshlrev_b64 v[124:125], 16, v[208:209]
	v_lshl_add_u64 v[124:125], s[26:27], 0, v[124:125]
	v_lshl_add_u64 v[124:125], v[182:183], 4, v[124:125]
	global_store_dwordx4 v[124:125], v[120:123], off

; __device__ __forceinline__ unsigned cvt_pk_bf16(float lo, float hi) { unsigned r; asm volatile("v_cvt_pk_bf16_f32 %0, %1, %2" : "=v"(r) : "v"(lo), "v"(hi)); return r; }
;     __device__ __forceinline__ void operator()(const f32x4 (&acc)[2][2][4][2], const Unit& u, int wr, int wc, int fr, int fq) const {
;     ...
;                 for (int bj = 0; bj < 2; ++bj) { f32x4 v0 = acc[ai][bj][m][0], v1 = acc[ai][bj][m][1];
;                     if (ACT == 2) {
; #pragma unroll
;                         for (int e = 0; e < 4; ++e) { const float a = fmaxf(v0[e], 0.f), b = fmaxf(v1[e], 0.f); v0[e] = a * a; v1[e] = b * b; } }
;                     v0 = v0 * f; v1 = v1 * f; u32x4 w; w.x = cvt_pk_bf16(v0[0], v0[1]); w.y = cvt_pk_bf16(v0[2], v0[3]); w.z = cvt_pk_bf16(v1[0], v1[1]); w.w = cvt_pk_bf16(v1[2], v1[3]);
;                     if (kplane) *(u32x4*)(base + ((size_t)(((colt >> 6) + 2 * bj + (wc >> 1)) * 8 + (wc & 1) * 4 + fq) * kprows + row) * 8) = w;
.LBB0_154:
	s_andn2_b64 vcc, exec, s[28:29]
	v_lshl_or_b32 v116, s6, 3, v193
	v_add_u32_e32 v116, v219, v116
	s_cbranch_vccnz .LBB0_156
	v_mov_b32_e32 v117, v209
	v_lshlrev_b64 v[118:119], 16, v[116:117]
	v_lshl_add_u64 v[118:119], s[26:27], 0, v[118:119]
	v_lshl_add_u64 v[118:119], v[182:183], 4, v[118:119]
	global_store_dwordx4 v[118:119], v[112:115], off

; __device__ __forceinline__ unsigned cvt_pk_bf16(float lo, float hi) { unsigned r; asm volatile("v_cvt_pk_bf16_f32 %0, %1, %2" : "=v"(r) : "v"(lo), "v"(hi)); return r; }
;     __device__ __forceinline__ void operator()(const f32x4 (&acc)[2][2][4][2], const Unit& u, int wr, int wc, int fr, int fq) const {
;     ...
;                 for (int bj = 0; bj < 2; ++bj) { f32x4 v0 = acc[ai][bj][m][0], v1 = acc[ai][bj][m][1];
;                     if (ACT == 2) {
; #pragma unroll
;                         for (int e = 0; e < 4; ++e) { const float a = fmaxf(v0[e], 0.f), b = fmaxf(v1[e], 0.f); v0[e] = a * a; v1[e] = b * b; } }
;                     v0 = v0 * f; v1 = v1 * f; u32x4 w; w.x = cvt_pk_bf16(v0[0], v0[1]); w.y = cvt_pk_bf16(v0[2], v0[3]); w.z = cvt_pk_bf16(v1[0], v1[1]); w.w = cvt_pk_bf16(v1[2], v1[3]);
;                     if (kplane) *(u32x4*)(base + ((size_t)(((colt >> 6) + 2 * bj + (wc >> 1)) * 8 + (wc & 1) * 4 + fq) * kprows + row) * 8) = w;
.LBB0_158:
	s_andn2_b64 vcc, exec, s[28:29]
	s_cbranch_vccnz .LBB0_160
	v_lshlrev_b64 v[108:109], 16, v[208:209]
	v_lshl_add_u64 v[108:109], s[26:27], 0, v[108:109]
	v_lshl_add_u64 v[108:109], v[180:181], 4, v[108:109]
	global_store_dwordx4 v[108:109], v[104:107], off

; __device__ __forceinline__ unsigned cvt_pk_bf16(float lo, float hi) { unsigned r; asm volatile("v_cvt_pk_bf16_f32 %0, %1, %2" : "=v"(r) : "v"(lo), "v"(hi)); return r; }
;     __device__ __forceinline__ void operator()(const f32x4 (&acc)[2][2][4][2], const Unit& u, int wr, int wc, int fr, int fq) const {
;     ...
;                 for (int bj = 0; bj < 2; ++bj) { f32x4 v0 = acc[ai][bj][m][0], v1 = acc[ai][bj][m][1];
;                     if (ACT == 2) {
; #pragma unroll
;                         for (int e = 0; e < 4; ++e) { const float a = fmaxf(v0[e], 0.f), b = fmaxf(v1[e], 0.f); v0[e] = a * a; v1[e] = b * b; } }
;                     v0 = v0 * f; v1 = v1 * f; u32x4 w; w.x = cvt_pk_bf16(v0[0], v0[1]); w.y = cvt_pk_bf16(v0[2], v0[3]); w.z = cvt_pk_bf16(v1[0], v1[1]); w.w = cvt_pk_bf16(v1[2], v1[3]);
;                     if (kplane) *(u32x4*)(base + ((size_t)(((colt >> 6) + 2 * bj + (wc >> 1)) * 8 + (wc & 1) * 4 + fq) * kprows + row) * 8) = w;
.LBB0_162:
	s_andn2_b64 vcc, exec, s[28:29]
	s_cbranch_vccnz .LBB0_164
	v_mov_b32_e32 v117, v209
	v_lshlrev_b64 v[100:101], 16, v[116:117]
	v_lshl_add_u64 v[100:101], s[26:27], 0, v[100:101]
	v_lshl_add_u64 v[100:101], v[180:181], 4, v[100:101]
	global_store_dwordx4 v[100:101], v[96:99], off

; __device__ __forceinline__ unsigned cvt_pk_bf16(float lo, float hi) { unsigned r; asm volatile("v_cvt_pk_bf16_f32 %0, %1, %2" : "=v"(r) : "v"(lo), "v"(hi)); return r; }
;     __device__ __forceinline__ void operator()(const f32x4 (&acc)[2][2][4][2], const Unit& u, int wr, int wc, int fr, int fq) const {
;     ...
;                 for (int bj = 0; bj < 2; ++bj) { f32x4 v0 = acc[ai][bj][m][0], v1 = acc[ai][bj][m][1];
;                     if (ACT == 2) {
; #pragma unroll
;                         for (int e = 0; e < 4; ++e) { const float a = fmaxf(v0[e], 0.f), b = fmaxf(v1[e], 0.f); v0[e] = a * a; v1[e] = b * b; } }
;                     v0 = v0 * f; v1 = v1 * f; u32x4 w; w.x = cvt_pk_bf16(v0[0], v0[1]); w.y = cvt_pk_bf16(v0[2], v0[3]); w.z = cvt_pk_bf16(v1[0], v1[1]); w.w = cvt_pk_bf16(v1[2], v1[3]);
;                     if (kplane) *(u32x4*)(base + ((size_t)(((colt >> 6) + 2 * bj + (wc >> 1)) * 8 + (wc & 1) * 4 + fq) * kprows + row) * 8) = w;
.LBB0_166:
	s_andn2_b64 vcc, exec, s[28:29]
	s_cbranch_vccnz .LBB0_168
	v_lshlrev_b64 v[92:93], 16, v[208:209]
	v_lshl_add_u64 v[92:93], s[26:27], 0, v[92:93]
	v_lshl_add_u64 v[92:93], v[178:179], 4, v[92:93]
	global_store_dwordx4 v[92:93], v[88:91], off

; __device__ __forceinline__ unsigned cvt_pk_bf16(float lo, float hi) { unsigned r; asm volatile("v_cvt_pk_bf16_f32 %0, %1, %2" : "=v"(r) : "v"(lo), "v"(hi)); return r; }
;     __device__ __forceinline__ void operator()(const f32x4 (&acc)[2][2][4][2], const Unit& u, int wr, int wc, int fr, int fq) const {
;     ...
;                 for (int bj = 0; bj < 2; ++bj) { f32x4 v0 = acc[ai][bj][m][0], v1 = acc[ai][bj][m][1];
;                     if (ACT == 2) {
; #pragma unroll
;                         for (int e = 0; e < 4; ++e) { const float a = fmaxf(v0[e], 0.f), b = fmaxf(v1[e], 0.f); v0[e] = a * a; v1[e] = b * b; } }
;                     v0 = v0 * f; v1 = v1 * f; u32x4 w; w.x = cvt_pk_bf16(v0[0], v0[1]); w.y = cvt_pk_bf16(v0[2], v0[3]); w.z = cvt_pk_bf16(v1[0], v1[1]); w.w = cvt_pk_bf16(v1[2], v1[3]);
;                     if (kplane) *(u32x4*)(base + ((size_t)(((colt >> 6) + 2 * bj + (wc >> 1)) * 8 + (wc & 1) * 4 + fq) * kprows + row) * 8) = w;
.LBB0_170:
	s_andn2_b64 vcc, exec, s[28:29]
	s_cbranch_vccnz .LBB0_172
	v_mov_b32_e32 v117, v209
	v_lshlrev_b64 v[84:85], 16, v[116:117]
	v_lshl_add_u64 v[84:85], s[26:27], 0, v[84:85]
	v_lshl_add_u64 v[84:85], v[178:179], 4, v[84:85]
	global_store_dwordx4 v[84:85], v[80:83], off

; __device__ __forceinline__ unsigned cvt_pk_bf16(float lo, float hi) { unsigned r; asm volatile("v_cvt_pk_bf16_f32 %0, %1, %2" : "=v"(r) : "v"(lo), "v"(hi)); return r; }
;     __device__ __forceinline__ void operator()(const f32x4 (&acc)[2][2][4][2], const Unit& u, int wr, int wc, int fr, int fq) const {
;     ...
;                 for (int bj = 0; bj < 2; ++bj) { f32x4 v0 = acc[ai][bj][m][0], v1 = acc[ai][bj][m][1];
;                     if (ACT == 2) {
; #pragma unroll
;                         for (int e = 0; e < 4; ++e) { const float a = fmaxf(v0[e], 0.f), b = fmaxf(v1[e], 0.f); v0[e] = a * a; v1[e] = b * b; } }
;                     v0 = v0 * f; v1 = v1 * f; u32x4 w; w.x = cvt_pk_bf16(v0[0], v0[1]); w.y = cvt_pk_bf16(v0[2], v0[3]); w.z = cvt_pk_bf16(v1[0], v1[1]); w.w = cvt_pk_bf16(v1[2], v1[3]);
;                     if (kplane) *(u32x4*)(base + ((size_t)(((colt >> 6) + 2 * bj + (wc >> 1)) * 8 + (wc & 1) * 4 + fq) * kprows + row) * 8) = w;
.LBB0_174:
	s_andn2_b64 vcc, exec, s[28:29]
	s_cbranch_vccnz .LBB0_176
	v_lshlrev_b64 v[76:77], 16, v[208:209]
	v_lshl_add_u64 v[76:77], s[26:27], 0, v[76:77]
	v_lshl_add_u64 v[76:77], v[176:177], 4, v[76:77]
	global_store_dwordx4 v[76:77], v[72:75], off

; __device__ __forceinline__ unsigned cvt_pk_bf16(float lo, float hi) { unsigned r; asm volatile("v_cvt_pk_bf16_f32 %0, %1, %2" : "=v"(r) : "v"(lo), "v"(hi)); return r; }
;     __device__ __forceinline__ void operator()(const f32x4 (&acc)[2][2][4][2], const Unit& u, int wr, int wc, int fr, int fq) const {
;     ...
;                 for (int bj = 0; bj < 2; ++bj) { f32x4 v0 = acc[ai][bj][m][0], v1 = acc[ai][bj][m][1];
;                     if (ACT == 2) {
; #pragma unroll
;                         for (int e = 0; e < 4; ++e) { const float a = fmaxf(v0[e], 0.f), b = fmaxf(v1[e], 0.f); v0[e] = a * a; v1[e] = b * b; } }
;                     v0 = v0 * f; v1 = v1 * f; u32x4 w; w.x = cvt_pk_bf16(v0[0], v0[1]); w.y = cvt_pk_bf16(v0[2], v0[3]); w.z = cvt_pk_bf16(v1[0], v1[1]); w.w = cvt_pk_bf16(v1[2], v1[3]);
;                     if (kplane) *(u32x4*)(base + ((size_t)(((colt >> 6) + 2 * bj + (wc >> 1)) * 8 + (wc & 1) * 4 + fq) * kprows + row) * 8) = w;
.LBB0_178:
	s_andn2_b64 vcc, exec, s[28:29]
	s_cbranch_vccnz .LBB0_180
	v_mov_b32_e32 v117, v209
	v_lshlrev_b64 v[68:69], 16, v[116:117]
	v_lshl_add_u64 v[68:69], s[26:27], 0, v[68:69]
	v_lshl_add_u64 v[68:69], v[176:177], 4, v[68:69]
	global_store_dwordx4 v[68:69], v[64:67], off

; __device__ __forceinline__ unsigned cvt_pk_bf16(float lo, float hi) { unsigned r; asm volatile("v_cvt_pk_bf16_f32 %0, %1, %2" : "=v"(r) : "v"(lo), "v"(hi)); return r; }
;     __device__ __forceinline__ void operator()(const f32x4 (&acc)[2][2][4][2], const Unit& u, int wr, int wc, int fr, int fq) const {
;     ...
;                 for (int bj = 0; bj < 2; ++bj) { f32x4 v0 = acc[ai][bj][m][0], v1 = acc[ai][bj][m][1];
;                     if (ACT == 2) {
; #pragma unroll
;                         for (int e = 0; e < 4; ++e) { const float a = fmaxf(v0[e], 0.f), b = fmaxf(v1[e], 0.f); v0[e] = a * a; v1[e] = b * b; } }
;                     v0 = v0 * f; v1 = v1 * f; u32x4 w; w.x = cvt_pk_bf16(v0[0], v0[1]); w.y = cvt_pk_bf16(v0[2], v0[3]); w.z = cvt_pk_bf16(v1[0], v1[1]); w.w = cvt_pk_bf16(v1[2], v1[3]);
;                     if (kplane) *(u32x4*)(base + ((size_t)(((colt >> 6) + 2 * bj + (wc >> 1)) * 8 + (wc & 1) * 4 + fq) * kprows + row) * 8) = w;
.LBB0_182:
	s_andn2_b64 vcc, exec, s[28:29]
	s_cbranch_vccnz .LBB0_184
	v_lshlrev_b64 v[60:61], 16, v[208:209]
	v_lshl_add_u64 v[60:61], s[26:27], 0, v[60:61]
	v_lshl_add_u64 v[60:61], v[174:175], 4, v[60:61]
	global_store_dwordx4 v[60:61], v[56:59], off

; __device__ __forceinline__ unsigned cvt_pk_bf16(float lo, float hi) { unsigned r; asm volatile("v_cvt_pk_bf16_f32 %0, %1, %2" : "=v"(r) : "v"(lo), "v"(hi)); return r; }
;     __device__ __forceinline__ void operator()(const f32x4 (&acc)[2][2][4][2], const Unit& u, int wr, int wc, int fr, int fq) const {
;     ...
;                 for (int bj = 0; bj < 2; ++bj) { f32x4 v0 = acc[ai][bj][m][0], v1 = acc[ai][bj][m][1];
;                     if (ACT == 2) {
; #pragma unroll
;                         for (int e = 0; e < 4; ++e) { const float a = fmaxf(v0[e], 0.f), b = fmaxf(v1[e], 0.f); v0[e] = a * a; v1[e] = b * b; } }
;                     v0 = v0 * f; v1 = v1 * f; u32x4 w; w.x = cvt_pk_bf16(v0[0], v0[1]); w.y = cvt_pk_bf16(v0[2], v0[3]); w.z = cvt_pk_bf16(v1[0], v1[1]); w.w = cvt_pk_bf16(v1[2], v1[3]);
;                     if (kplane) *(u32x4*)(base + ((size_t)(((colt >> 6) + 2 * bj + (wc >> 1)) * 8 + (wc & 1) * 4 + fq) * kprows + row) * 8) = w;
.LBB0_186:
	s_andn2_b64 vcc, exec, s[28:29]
	s_cbranch_vccnz .LBB0_188
	v_mov_b32_e32 v117, v209
	v_lshlrev_b64 v[52:53], 16, v[116:117]
	v_lshl_add_u64 v[52:53], s[26:27], 0, v[52:53]
	v_lshl_add_u64 v[52:53], v[174:175], 4, v[52:53]
	global_store_dwordx4 v[52:53], v[48:51], off

; __device__ __forceinline__ unsigned cvt_pk_bf16(float lo, float hi) { unsigned r; asm volatile("v_cvt_pk_bf16_f32 %0, %1, %2" : "=v"(r) : "v"(lo), "v"(hi)); return r; }
;     __device__ __forceinline__ void operator()(const f32x4 (&acc)[2][2][4][2], const Unit& u, int wr, int wc, int fr, int fq) const {
;     ...
;                 for (int bj = 0; bj < 2; ++bj) { f32x4 v0 = acc[ai][bj][m][0], v1 = acc[ai][bj][m][1];
;                     if (ACT == 2) {
; #pragma unroll
;                         for (int e = 0; e < 4; ++e) { const float a = fmaxf(v0[e], 0.f), b = fmaxf(v1[e], 0.f); v0[e] = a * a; v1[e] = b * b; } }
;                     v0 = v0 * f; v1 = v1 * f; u32x4 w; w.x = cvt_pk_bf16(v0[0], v0[1]); w.y = cvt_pk_bf16(v0[2], v0[3]); w.z = cvt_pk_bf16(v1[0], v1[1]); w.w = cvt_pk_bf16(v1[2], v1[3]);
;                     if (kplane) *(u32x4*)(base + ((size_t)(((colt >> 6) + 2 * bj + (wc >> 1)) * 8 + (wc & 1) * 4 + fq) * kprows + row) * 8) = w;
.LBB0_190:
	s_andn2_b64 vcc, exec, s[28:29]
	s_cbranch_vccnz .LBB0_192
	v_lshlrev_b64 v[44:45], 16, v[208:209]
	v_lshl_add_u64 v[44:45], s[26:27], 0, v[44:45]
	v_lshl_add_u64 v[44:45], v[172:173], 4, v[44:45]
	global_store_dwordx4 v[44:45], v[40:43], off

; __device__ __forceinline__ unsigned cvt_pk_bf16(float lo, float hi) { unsigned r; asm volatile("v_cvt_pk_bf16_f32 %0, %1, %2" : "=v"(r) : "v"(lo), "v"(hi)); return r; }
;     __device__ __forceinline__ void operator()(const f32x4 (&acc)[2][2][4][2], const Unit& u, int wr, int wc, int fr, int fq) const {
;     ...
;                 for (int bj = 0; bj < 2; ++bj) { f32x4 v0 = acc[ai][bj][m][0], v1 = acc[ai][bj][m][1];
;                     if (ACT == 2) {
; #pragma unroll
;                         for (int e = 0; e < 4; ++e) { const float a = fmaxf(v0[e], 0.f), b = fmaxf(v1[e], 0.f); v0[e] = a * a; v1[e] = b * b; } }
;                     v0 = v0 * f; v1 = v1 * f; u32x4 w; w.x = cvt_pk_bf16(v0[0], v0[1]); w.y = cvt_pk_bf16(v0[2], v0[3]); w.z = cvt_pk_bf16(v1[0], v1[1]); w.w = cvt_pk_bf16(v1[2], v1[3]);
;                     if (kplane) *(u32x4*)(base + ((size_t)(((colt >> 6) + 2 * bj + (wc >> 1)) * 8 + (wc & 1) * 4 + fq) * kprows + row) * 8) = w;
.LBB0_194:
	s_andn2_b64 vcc, exec, s[28:29]
	s_cbranch_vccnz .LBB0_196
	v_mov_b32_e32 v117, v209
	v_lshlrev_b64 v[36:37], 16, v[116:117]
	v_lshl_add_u64 v[36:37], s[26:27], 0, v[36:37]
	v_lshl_add_u64 v[36:37], v[172:173], 4, v[36:37]
	global_store_dwordx4 v[36:37], v[32:35], off

; __device__ __forceinline__ unsigned cvt_pk_bf16(float lo, float hi) { unsigned r; asm volatile("v_cvt_pk_bf16_f32 %0, %1, %2" : "=v"(r) : "v"(lo), "v"(hi)); return r; }
;     __device__ __forceinline__ void operator()(const f32x4 (&acc)[2][2][4][2], const Unit& u, int wr, int wc, int fr, int fq) const {
;     ...
;                 for (int bj = 0; bj < 2; ++bj) { f32x4 v0 = acc[ai][bj][m][0], v1 = acc[ai][bj][m][1];
;                     if (ACT == 2) {
; #pragma unroll
;                         for (int e = 0; e < 4; ++e) { const float a = fmaxf(v0[e], 0.f), b = fmaxf(v1[e], 0.f); v0[e] = a * a; v1[e] = b * b; } }
;                     v0 = v0 * f; v1 = v1 * f; u32x4 w; w.x = cvt_pk_bf16(v0[0], v0[1]); w.y = cvt_pk_bf16(v0[2], v0[3]); w.z = cvt_pk_bf16(v1[0], v1[1]); w.w = cvt_pk_bf16(v1[2], v1[3]);
;                     if (kplane) *(u32x4*)(base + ((size_t)(((colt >> 6) + 2 * bj + (wc >> 1)) * 8 + (wc & 1) * 4 + fq) * kprows + row) * 8) = w;
.LBB0_198:
	s_andn2_b64 vcc, exec, s[28:29]
	s_cbranch_vccnz .LBB0_200
	v_lshlrev_b64 v[28:29], 16, v[208:209]
	v_lshl_add_u64 v[28:29], s[26:27], 0, v[28:29]
	v_lshl_add_u64 v[28:29], v[168:169], 4, v[28:29]
	global_store_dwordx4 v[28:29], v[24:27], off

; __device__ __forceinline__ unsigned cvt_pk_bf16(float lo, float hi) { unsigned r; asm volatile("v_cvt_pk_bf16_f32 %0, %1, %2" : "=v"(r) : "v"(lo), "v"(hi)); return r; }
;     __device__ __forceinline__ void operator()(const f32x4 (&acc)[2][2][4][2], const Unit& u, int wr, int wc, int fr, int fq) const {
;     ...
;                 for (int bj = 0; bj < 2; ++bj) { f32x4 v0 = acc[ai][bj][m][0], v1 = acc[ai][bj][m][1];
;                     if (ACT == 2) {
; #pragma unroll
;                         for (int e = 0; e < 4; ++e) { const float a = fmaxf(v0[e], 0.f), b = fmaxf(v1[e], 0.f); v0[e] = a * a; v1[e] = b * b; } }
;                     v0 = v0 * f; v1 = v1 * f; u32x4 w; w.x = cvt_pk_bf16(v0[0], v0[1]); w.y = cvt_pk_bf16(v0[2], v0[3]); w.z = cvt_pk_bf16(v1[0], v1[1]); w.w = cvt_pk_bf16(v1[2], v1[3]);
;                     if (kplane) *(u32x4*)(base + ((size_t)(((colt >> 6) + 2 * bj + (wc >> 1)) * 8 + (wc & 1) * 4 + fq) * kprows + row) * 8) = w;
.LBB0_202:
	s_andn2_b64 vcc, exec, s[28:29]
	s_cbranch_vccnz .LBB0_204
	v_mov_b32_e32 v117, v209
	v_lshlrev_b64 v[20:21], 16, v[116:117]
	v_lshl_add_u64 v[20:21], s[26:27], 0, v[20:21]
	v_lshl_add_u64 v[20:21], v[168:169], 4, v[20:21]
	global_store_dwordx4 v[20:21], v[16:19], off

; __device__ __forceinline__ unsigned cvt_pk_bf16(float lo, float hi) { unsigned r; asm volatile("v_cvt_pk_bf16_f32 %0, %1, %2" : "=v"(r) : "v"(lo), "v"(hi)); return r; }
;     __device__ __forceinline__ void operator()(const f32x4 (&acc)[2][2][4][2], const Unit& u, int wr, int wc, int fr, int fq) const {
;     ...
;                 for (int bj = 0; bj < 2; ++bj) { f32x4 v0 = acc[ai][bj][m][0], v1 = acc[ai][bj][m][1];
;                     if (ACT == 2) {
; #pragma unroll
;                         for (int e = 0; e < 4; ++e) { const float a = fmaxf(v0[e], 0.f), b = fmaxf(v1[e], 0.f); v0[e] = a * a; v1[e] = b * b; } }
;                     v0 = v0 * f; v1 = v1 * f; u32x4 w; w.x = cvt_pk_bf16(v0[0], v0[1]); w.y = cvt_pk_bf16(v0[2], v0[3]); w.z = cvt_pk_bf16(v1[0], v1[1]); w.w = cvt_pk_bf16(v1[2], v1[3]);
;                     if (kplane) *(u32x4*)(base + ((size_t)(((colt >> 6) + 2 * bj + (wc >> 1)) * 8 + (wc & 1) * 4 + fq) * kprows + row) * 8) = w;
.LBB0_206:
	s_andn2_b64 vcc, exec, s[28:29]
	s_cbranch_vccnz .LBB0_208
	v_lshlrev_b64 v[12:13], 16, v[208:209]
	v_lshl_add_u64 v[12:13], s[26:27], 0, v[12:13]
	v_lshl_add_u64 v[12:13], v[166:167], 4, v[12:13]
	global_store_dwordx4 v[12:13], v[8:11], off

; __device__ __forceinline__ unsigned cvt_pk_bf16(float lo, float hi) { unsigned r; asm volatile("v_cvt_pk_bf16_f32 %0, %1, %2" : "=v"(r) : "v"(lo), "v"(hi)); return r; }
;     __device__ __forceinline__ void operator()(const f32x4 (&acc)[2][2][4][2], const Unit& u, int wr, int wc, int fr, int fq) const {
;     ...
;                 for (int bj = 0; bj < 2; ++bj) { f32x4 v0 = acc[ai][bj][m][0], v1 = acc[ai][bj][m][1];
;                     if (ACT == 2) {
; #pragma unroll
;                         for (int e = 0; e < 4; ++e) { const float a = fmaxf(v0[e], 0.f), b = fmaxf(v1[e], 0.f); v0[e] = a * a; v1[e] = b * b; } }
;                     v0 = v0 * f; v1 = v1 * f; u32x4 w; w.x = cvt_pk_bf16(v0[0], v0[1]); w.y = cvt_pk_bf16(v0[2], v0[3]); w.z = cvt_pk_bf16(v1[0], v1[1]); w.w = cvt_pk_bf16(v1[2], v1[3]);
;                     if (kplane) *(u32x4*)(base + ((size_t)(((colt >> 6) + 2 * bj + (wc >> 1)) * 8 + (wc & 1) * 4 + fq) * kprows + row) * 8) = w;
; template <class Epi, class Sched, bool ALIGN_EPI = false, bool SP2 = false>
; __device__ __forceinline__ void gemm_phase(PG8_LAS unsigned char* lds, const Gemm g, const Sched& S, const Epi& E, const int tid_in) {
;     ...
;         if (!has_next) break;
.LBB0_212:
	v_mov_b32_e32 v117, v209
	v_lshlrev_b64 v[4:5], 16, v[116:117]
	v_lshl_add_u64 v[4:5], s[26:27], 0, v[4:5]
	v_lshl_add_u64 v[4:5], v[166:167], 4, v[4:5]
	global_store_dwordx4 v[4:5], v[0:3], off
	s_and_b64 vcc, exec, s[38:39]
	s_mov_b64 s[26:27], -1
	s_cbranch_vccnz .LBB0_136

; #define PG8_STAGE(bufoff, gbase, voff) do { _Pragma("unroll") for (int _i = 0; _i < 2; ++_i) \
;         __builtin_amdgcn_global_load_lds((const unsigned*)((const char*)(gbase) + (voff)[_i]), (PG8_LAS unsigned*)(lds + (bufoff) + ldsw + _i * 8192), 16, 0, 0); } while (0)
; #define PG8_WAIT_V(n) asm volatile("s_waitcnt vmcnt(" #n ")" ::: "memory")
; #define PG8_BAR __builtin_amdgcn_s_barrier()
;     __host__ __device__ bool next(int i, Unit& u) const {
;         long L = (long)i * G + c; if (L >= nwg) return false;
;         if (rev) L = nwg - 1 - L;
;         int wgid = (int)L; { const int q = nwg / NXCD, r = nwg % NXCD, xcd = wgid % NXCD, off = wgid / NXCD; wgid = (xcd < r ? xcd * (q + 1) : r * (q + 1) + (xcd - r) * q) + off; }
;         const int nig = WGM * nN, gid = wgid / nig, fm = gid * WGM, gsz = (nM - fm) < WGM ? (nM - fm) : WGM;
;         u.pm = fm + ((wgid % nig) % gsz); u.pn = (wgid % nig) / gsz; return true;
;     }
; template <class Epi, class Sched, bool ALIGN_EPI = false, bool SP2 = false>
; __device__ __forceinline__ void gemm_phase(PG8_LAS unsigned char* lds, const Gemm g, const Sched& S, const Epi& E, const int tid_in) {
;     ...
;     const char* cA = (const char*)g.A + (size_t)cur.pm * tstepA + (size_t)cur.pn * g.a_pn_stride; const char* cB = (const char*)g.Bt + (size_t)cur.pn * tstepB;
;     S.a_ready(cur);
;     if constexpr (SP2) {
;         PG8_STAGE(PG8_SB(0, 0), cB, voffB); PG8_STAGE(PG8_SB(0, 1), cB + hstepB, voffB); PG8_STAGE(PG8_SA(0, 0), cA, voffA); PG8_STAGE(PG8_SA(0, 1), cA + hstepA, voffA);
;         if (wr == 1) PG8_BAR;
;         PG8_WAIT_V(2); PG8_BAR;
;         PG8_STAGE(PG8_SB(1, 0), cB + kstepB, voffB); PG8_STAGE(PG8_SA(1, 0), cA + kstepA, voffA); PG8_STAGE(PG8_SB(1, 1), cB + hstepB + kstepB, voffB);
;         PG8_WAIT_V(6); PG8_BAR;
;     } else {
;         PG8_STAGE(PG8_SB(0, 0), cB, voffB); PG8_STAGE(PG8_SA(0, 0), cA, voffA); PG8_STAGE(PG8_SB(0, 1), cB + hstepB, voffB); PG8_STAGE(PG8_SA(0, 1), cA + hstepA, voffA);
;         if (wr == 1) PG8_BAR;
;         PG8_WAIT_V(4); PG8_BAR;
;         PG8_STAGE(PG8_SB(1, 0), cB + kstepB, voffB); PG8_STAGE(PG8_SA(1, 0), cA + kstepA, voffA); PG8_STAGE(PG8_SB(1, 1), cB + hstepB + kstepB, voffB);
;         PG8_WAIT_V(6); PG8_BAR;
;     }
.LBB0_217:
	s_andn2_b64 vcc, exec, s[10:11]
	s_cbranch_vccnz .LBB0_361
	s_load_dwordx2 s[8:9], s[14:15], 0x78
	v_readfirstlane_b32 s18, v188
	s_waitcnt lgkmcnt(0)
	s_ashr_i32 s0, s8, 31
	s_lshr_b32 s0, s0, 24
	s_add_i32 s0, s8, s0
	s_ashr_i32 s6, s0, 8
	s_lshl_b32 s8, s6, 7
	s_cmp_lt_i32 s2, s8
	s_cselect_b64 s[10:11], -1, 0
	s_cmp_ge_i32 s2, s8
	s_cbranch_scc1 .LBB0_220
	s_lshl_b32 s5, s6, 3
	s_abs_i32 s7, s5
	v_cvt_f32_u32_e32 v0, s7
	s_not_b32 s0, s2
	s_add_i32 s0, s8, s0
	s_ashr_i32 s3, s0, 31
	v_rcp_iflag_f32_e32 v0, v0
	s_lshr_b32 s3, s3, 29
	s_add_i32 s3, s0, s3
	s_ashr_i32 s4, s3, 3
	s_and_b32 s3, s3, -8
	v_mul_f32_e32 v0, 0x4f7ffffe, v0
	s_sub_i32 s0, s0, s3
	v_readlane_b32 s3, v255, 20
	s_xor_b32 s0, s0, s3
	v_cvt_u32_f32_e32 v0, v0
	s_lshl_b32 s1, s6, 4
	s_lshr_b32 s3, s0, 31
	s_or_b32 s1, s1, s3
	s_mul_i32 s0, s1, s0
	s_add_i32 s0, s0, s4
	s_sub_i32 s4, 0, s7
	v_readfirstlane_b32 s12, v0
	s_mul_i32 s4, s4, s12
	s_mul_hi_u32 s4, s12, s4
	s_abs_i32 s3, s0
	s_add_i32 s12, s12, s4
	s_mul_hi_u32 s4, s3, s12
	s_mul_i32 s12, s4, s7
	s_xor_b32 s1, s0, s5
	s_sub_i32 s3, s3, s12
	s_ashr_i32 s1, s1, 31
	s_add_i32 s12, s4, 1
	s_sub_i32 s13, s3, s7
	s_cmp_ge_u32 s3, s7
	s_cselect_b32 s4, s12, s4
	s_cselect_b32 s3, s13, s3
	s_add_i32 s12, s4, 1
	s_cmp_ge_u32 s3, s7
	s_cselect_b32 s3, s12, s4
	s_xor_b32 s3, s3, s1
	s_sub_i32 s1, s3, s1
	s_lshl_b32 s3, s1, 3
	s_sub_i32 s4, 0x80, s3
	s_min_i32 s4, s4, 8
	s_abs_i32 s7, s4
	v_cvt_f32_u32_e32 v0, s7
	s_sub_i32 s12, 0, s7
	s_mul_i32 s1, s1, s5
	s_sub_i32 s0, s0, s1
	v_rcp_iflag_f32_e32 v0, v0
	s_abs_i32 s5, s0
	s_xor_b32 s1, s0, s4
	s_ashr_i32 s1, s1, 31
	v_mul_f32_e32 v0, 0x4f7ffffe, v0
	v_cvt_u32_f32_e32 v0, v0
	s_mov_b64 s[16:17], s[14:15]
	v_readfirstlane_b32 s13, v0
	s_mul_i32 s12, s12, s13
	s_mul_hi_u32 s12, s13, s12
	s_add_i32 s13, s13, s12
	s_mul_hi_u32 s12, s5, s13
	s_mul_i32 s13, s12, s7
	s_sub_i32 s5, s5, s13
	s_add_i32 s13, s12, 1
	s_sub_i32 s14, s5, s7
	s_cmp_ge_u32 s5, s7
	s_cselect_b32 s12, s13, s12
	s_cselect_b32 s5, s14, s5
	s_add_i32 s13, s12, 1
	s_cmp_ge_u32 s5, s7
	s_cselect_b32 s5, s13, s12
	s_xor_b32 s5, s5, s1
	s_sub_i32 s33, s5, s1
	s_mul_i32 s1, s33, s4
	s_sub_i32 s0, s0, s1
	s_mov_b64 s[14:15], s[16:17]
	s_add_i32 s93, s0, s3
	s_bfe_u32 s72, s93, 0x20002
	s_lshl_b32 s72, s72, 5
	s_lshr_b32 s4, s93, 4
	s_lshl_b32 s4, s4, 2
	s_or_b32 s72, s72, s4
	s_and_b32 s4, s93, 3
	s_or_b32 s72, s72, s4
	s_cmpk_eq_i32 s9, 0x1000
	s_cselect_b32 s72, s72, s93
.LBB0_220:
	s_andn2_b64 vcc, exec, s[10:11]
	s_cbranch_vccnz .LBB0_361
	v_bfe_i32 v1, v188, 27, 1
	v_lshlrev_b32_e32 v208, 4, v188
	v_lshrrev_b32_e32 v1, 22, v1
	v_add_u32_e32 v1, v208, v1
	v_and_b32_e32 v1, 0xfffffc00, v1
	v_sub_u32_e32 v1, v208, v1
	v_lshrrev_b32_e32 v2, 4, v1
	v_ashrrev_i32_e32 v0, 31, v188
	v_bitop3_b32 v1, v2, v1, 32 bitop3:0x6c
	s_cmpk_eq_i32 s9, 0x1000
	v_lshrrev_b32_e32 v0, 26, v0
	v_ashrrev_i32_e32 v3, 31, v1
	s_load_dwordx4 s[56:59], s[14:15], 0x88
	s_load_dwordx2 s[10:11], s[14:15], 0xb0
	v_add_u32_e32 v0, v188, v0
	v_lshrrev_b32_e32 v3, 26, v3
	s_cselect_b64 vcc, -1, 0
	s_ashr_i32 s23, s9, 31
	v_ashrrev_i32_e32 v0, 6, v0
	v_add_u32_e32 v3, v1, v3
	s_lshr_b32 s3, s23, 26
	v_lshlrev_b32_e32 v2, 3, v0
	v_ashrrev_i32_e32 v4, 6, v3
	v_and_b32_e32 v3, 0xc0, v3
	s_add_i32 s3, s9, s3
	s_mov_b32 s22, s9
	v_and_b32_e32 v2, 0x7ffffff0, v2
	v_lshlrev_b32_e32 v0, 5, v0
	v_sub_u32_e32 v1, v1, v3
	v_mov_b32_e32 v5, 1
	s_ashr_i32 s12, s3, 6
	s_lshl_b64 s[20:21], s[22:23], 9
	s_ashr_i32 s3, s93, 31
	v_add_u32_e32 v2, v4, v2
	v_and_b32_e32 v0, 32, v0
	v_ashrrev_i16_sdwa v1, v5, sext(v1) dst_sel:DWORD dst_unused:UNUSED_PAD src0_sel:DWORD src1_sel:BYTE_0
	s_ashr_i32 s0, s18, 6
	v_writelane_b32 v255, s18, 5
	s_ashr_i32 s1, s18, 8
	s_lshl_b64 s[18:19], s[22:23], 8
	s_mul_i32 s3, s20, s3
	s_mul_hi_u32 s4, s20, s72
	s_lshr_b64 s[22:23], s[22:23], 23
	s_ashr_i32 s5, s33, 31
	v_mul_lo_u32 v2, s9, v2
	v_add_u32_sdwa v0, v0, sext(v1) dst_sel:DWORD dst_unused:UNUSED_PAD src0_sel:DWORD src1_sel:WORD_0
	s_ashr_i32 s13, s12, 31
	s_add_i32 s3, s4, s3
	s_mul_i32 s4, s22, s72
	s_waitcnt lgkmcnt(0)
	s_mul_hi_u32 s7, s10, s33
	s_mul_i32 s22, s10, s5
	v_add_lshl_u32 v0, v0, v2, 1
	v_add_u32_e32 v212, 0x2000, v208
	s_lshl_b64 s[16:17], s[12:13], 15
	s_add_i32 s7, s7, s22
	s_mul_i32 s22, s11, s33
	v_cndmask_b32_e32 v210, v0, v208, vcc
	v_ashrrev_i32_e32 v0, 31, v212
	s_add_i32 s7, s7, s22
	s_mul_i32 s5, s16, s5
	s_mul_hi_u32 s22, s16, s33
	v_lshrrev_b32_e32 v0, 22, v0
	s_add_i32 s5, s22, s5
	s_lshr_b64 s[22:23], s[12:13], 17
	v_add_u32_e32 v0, v212, v0
	s_mov_b64 s[28:29], s[14:15]
	s_lshl_b64 s[14:15], s[12:13], 14
	s_mul_i32 s13, s22, s33
	v_ashrrev_i32_e32 v0, 10, v0
	s_lshl_b32 s50, s0, 10
	s_add_i32 s3, s3, s4
	s_add_i32 s5, s5, s13
	s_mul_i32 s13, s16, s33
	v_mul_i32_i24_e32 v1, 0x400, v0
	s_add_u32 s48, s56, s13
	v_sub_u32_e32 v1, v212, v1
	s_addc_u32 s49, s57, s5
	s_add_i32 s13, s50, 0
	v_lshrrev_b32_e32 v2, 4, v1
	s_add_i32 m0, s13, 0x10000
	v_bitop3_b32 v1, v2, v1, 32 bitop3:0x6c
	s_mul_i32 s4, s20, s72
	global_load_lds_dwordx4 v208, s[48:49]
	s_add_i32 m0, s13, 0x12000
	v_readlane_b32 s22, v255, 2
	v_ashrrev_i32_e32 v3, 31, v1
	v_readlane_b32 s23, v255, 3
	s_add_u32 s4, s22, s4
	v_lshrrev_b32_e32 v3, 26, v3
	s_addc_u32 s3, s23, s3
	v_add_u32_e32 v3, v1, v3
	s_add_u32 s26, s48, s14
	v_lshlrev_b32_e32 v2, 3, v0
	v_ashrrev_i32_e32 v4, 6, v3
	v_and_b32_e32 v3, 0xc0, v3
	global_load_lds_dwordx4 v212, s[48:49]
	s_addc_u32 s27, s49, s15
	s_add_i32 m0, s13, 0x14000
	v_and_b32_e32 v2, 0x7ffffff0, v2
	v_lshlrev_b32_e32 v0, 5, v0
	v_sub_u32_e32 v1, v1, v3
	s_mul_i32 s24, s10, s33
	global_load_lds_dwordx4 v208, s[26:27]
	s_add_i32 m0, s13, 0x16000
	v_add_u32_e32 v2, v4, v2
	v_and_b32_e32 v0, 32, v0
	v_ashrrev_i16_sdwa v1, v5, sext(v1) dst_sel:DWORD dst_unused:UNUSED_PAD src0_sel:DWORD src1_sel:BYTE_0
	s_add_u32 s46, s4, s24
	v_mul_lo_u32 v2, s9, v2
	v_add_u32_sdwa v0, v0, sext(v1) dst_sel:DWORD dst_unused:UNUSED_PAD src0_sel:DWORD src1_sel:WORD_0
	s_addc_u32 s47, s3, s7
	s_add_i32 s51, s13, 0x2000
	v_add_lshl_u32 v0, v0, v2, 1
	global_load_lds_dwordx4 v212, s[26:27]
	s_mov_b32 m0, s13
	s_add_u32 s22, s46, s18
	v_cndmask_b32_e32 v214, v0, v212, vcc
	global_load_lds_dwordx4 v210, s[46:47]
	s_mov_b32 m0, s51
	s_addc_u32 s23, s47, s19
	s_add_i32 s64, s13, 0x4000
	global_load_lds_dwordx4 v214, s[46:47]
	s_mov_b32 m0, s64
	s_add_i32 s86, s13, 0x6000
	global_load_lds_dwordx4 v210, s[22:23]
	s_mov_b32 m0, s86
	v_writelane_b32 v255, s28, 6
	global_load_lds_dwordx4 v214, s[22:23]
	s_load_dwordx4 s[60:63], s[28:29], 0xa0
	v_writelane_b32 v255, s29, 7
	s_cmp_lg_u32 s1, 1
	s_cbranch_scc1 .LBB0_223
	s_barrier

; template <class Epi, class Sched, bool ALIGN_EPI = false, bool SP2 = false>
; __device__ __forceinline__ void gemm_phase(PG8_LAS unsigned char* lds, const Gemm g, const Sched& S, const Epi& E, const int tid_in) {
;     ...
;         const bool has_next = S.next(ui + 1, nxt);
;         const char* nA = has_next ? (const char*)g.A + (size_t)nxt.pm * tstepA + (size_t)nxt.pn * g.a_pn_stride : cA; const char* nB = has_next ? (const char*)g.Bt + (size_t)nxt.pn * tstepB : cB;
.LBB0_228:
	v_cndmask_b32_e64 v0, 0, 1, s[42:43]
	v_cmp_ne_u32_e64 s[44:45], 1, v0
	s_andn2_b64 vcc, exec, s[42:43]
	s_mov_b64 s[62:63], s[46:47]
	s_cbranch_vccnz .LBB0_230
	s_bfe_u32 s6, s95, 0x20002
	s_lshl_b32 s6, s6, 5
	s_lshr_b32 s7, s95, 4
	s_lshl_b32 s7, s7, 2
	s_or_b32 s6, s6, s7
	s_and_b32 s7, s95, 3
	s_or_b32 s6, s6, s7
	s_cmpk_eq_i32 s91, 0x4000
	s_cselect_b32 s6, s6, s95
	s_ashr_i32 s4, s95, 31
	s_mul_hi_u32 s5, s20, s6
	s_mul_i32 s4, s20, s4
	s_add_i32 s4, s5, s4
	s_mul_i32 s5, s21, s6
	s_add_i32 s4, s4, s5
	s_mul_i32 s5, s20, s6
	v_readlane_b32 s6, v255, 2
	v_readlane_b32 s7, v255, 3
	s_add_u32 s5, s6, s5
	s_addc_u32 s4, s7, s4
	s_ashr_i32 s6, s84, 31
	s_mul_hi_u32 s7, s10, s84
	s_mul_i32 s6, s10, s6
	s_add_i32 s6, s7, s6
	s_mul_i32 s7, s11, s84
	s_add_i32 s6, s6, s7
	s_mul_i32 s7, s10, s84
	s_add_u32 s62, s5, s7
	s_addc_u32 s63, s4, s6

; __global__ void __launch_bounds__(NWAVES * 64, 2) fwd_megakernel(Args args) {
;     ...
;     for (int ph = 0; ph < NCHUNK * PPC; ++ph) {
;         int tid = threadIdx.x; asm volatile("" : "+v"(tid));
;         int G = gridDim.x, bx = blockIdx.x; asm volatile("" : "+s"(G), "+s"(bx));
;         const int lane = tid & 63, wave = __builtin_amdgcn_readfirstlane(tid >> 6);
;         const int vcu = (G % 8 == 0) ? (bx % 8) * (G / 8) + bx / 8 : bx;
;         const int gw = vcu * NWAVES + wave, NGW = G * NWAVES;
.LBB0_358:
	s_waitcnt vmcnt(0)
	v_readlane_b32 s0, v255, 5
	v_readlane_b32 s74, v254, 1
	v_readlane_b32 s82, v254, 5
	v_readlane_b32 s84, v254, 60
	v_readlane_b32 s68, v254, 55
	v_readlane_b32 s70, v254, 57
	s_cmpk_gt_u32 s0, 0xff
	v_readlane_b32 s72, v254, 0
	v_readlane_b32 s75, v254, 2
	v_readlane_b32 s76, v254, 3
	v_readlane_b32 s83, v254, 6
	v_readlane_b32 s73, v254, 59
	v_readlane_b32 s85, v254, 61
	v_readlane_b32 s69, v254, 56
	v_readlane_b32 s71, v254, 58
	s_mov_b32 s86, 0x40000
	s_mov_b32 s87, 0x41000
	s_movk_i32 s91, 0x3c0
	s_mov_b32 s95, 0xffffffe
	v_xor_b32_e32 v217, 8, v232
	v_readlane_b32 s77, v254, 4
	s_cbranch_scc1 .LBB0_360

; __device__ __forceinline__ void xcd_barrier(const XcdBarrier& b) {
;     asm volatile("s_waitcnt vmcnt(0)" ::: "memory");
;     __syncthreads();
;     if (threadIdx.x == 0) {
;         unsigned* bar = b.bar;
;         __builtin_amdgcn_s_waitcnt(0);
;         unsigned nloc = b.st[0], nx = b.st[1];
;         if (nloc == 0u) { xcd_barrier_complete(bar, b.x, nloc, nx); b.st[0] = nloc; b.st[1] = nx; }
; __global__ void __launch_bounds__(NWAVES * 64, 2) fwd_megakernel(Args args) {
;     ...
;         if (d.kind != K_FINAL) xcd_barrier(bar);
.LBB0_475:
	s_load_dword s0, s[14:15], 0x70
	v_readlane_b32 s20, v254, 62
	v_readlane_b32 s21, v254, 63
	s_waitcnt lgkmcnt(0)
	s_cmp_eq_u32 s0, 7
	s_cbranch_scc1 .LBB0_64
	s_waitcnt vmcnt(0)
	s_waitcnt vmcnt(0)
	s_barrier
	s_and_saveexec_b64 s[4:5], s[82:83]
	s_cbranch_execz .LBB0_63
	s_and_b32 s0, s88, 0xff
	s_mul_i32 s0, s0, 27
	s_lshr_b32 s0, s0, 9
	s_mul_i32 s0, s0, 19
	s_sub_i32 s0, s88, s0
	s_lshr_b32 s0, 0, s0
	s_andn2_b32 s0, 1, s0
	v_readlane_b32 s1, v255, 20
	s_cmp_lg_u32 s1, 0
	s_cselect_b32 s0, s0, 0
	v_writelane_b32 v255, s0, 26
	v_readlane_b32 s0, v254, 53
	s_waitcnt vmcnt(0) expcnt(0) lgkmcnt(0)
	s_nop 0
	v_mov_b32_e32 v0, s0
	ds_read_b32 v2, v0
	v_readlane_b32 s0, v254, 54
	s_waitcnt lgkmcnt(0)
	v_cmp_ne_u32_e32 vcc, 0, v2
	v_mov_b32_e32 v0, s0
	ds_read_b32 v0, v0
	s_cbranch_vccnz .LBB0_492
	s_mov_b32 s0, 1
	s_branch .LBB0_480
